# retention-output items: one wave per state half prefetches the item's chunk-state cache lines into L2 right after the staging barrier (16 junk dword loads) so the 64 state-fragment loads later hit L2
# baseline (speedup 1.0000x reference)
; #define LAS __attribute__((address_space(3)))
; __device__ __forceinline__ int opaque_tid() { int t = threadIdx.x; asm volatile("" : "+v"(t)); return t; }
; __device__ void ret_out_item(const bf16_t* __restrict__ Qb, const bf16_t* __restrict__ Kb, bf16_t* Vb, const bf16_t* __restrict__ STf, const bf16_t* __restrict__ STb,
;                              int cidx, int head, float lgf2, float lgb2, LAS unsigned char* lds) {
;   const int tid = opaque_tid(), w = tid >> 6, l = tid & 63; const int row0 = cidx * 128;
;   constexpr unsigned VS = 576, ORED = 73728, QS = 272, OQ = 74752, OK = 74752 + 34816;
; #pragma unroll
;   for (int it = 0; it < 8; ++it) { const int q = tid + it * 512, j = q >> 5, c = q & 31;
;     *(LAS u32x4*)(lds + j * VS + c * 16) = *(const u32x4*)(Vb + (size_t)(row0 + j) * 1024 + head * 256 + c * 8); }
; #pragma unroll
;   for (int it = 0; it < 4; ++it) { const int q = tid + it * 512, j = q >> 4, c = q & 15;
;     *(LAS u32x4*)(lds + OQ + j * QS + c * 16) = *(const u32x4*)(Qb + (size_t)(row0 + j) * 512 + head * 128 + c * 8);
;     *(LAS u32x4*)(lds + OK + j * QS + c * 16) = *(const u32x4*)(Kb + (size_t)(row0 + j) * 512 + head * 128 + c * 8); }
;   __syncthreads();
.LBB0_642:
	v_mov_b32_e32 v24, v214
	s_and_b32 s13, s6, 0xffffff80
	v_add_u32_e32 v42, 0x200, v24
	s_lshl_b32 s12, s20, 8
	s_lshl_b32 s20, s20, 9
	v_ashrrev_i32_e32 v25, 5, v24
	v_ashrrev_i32_e32 v67, 5, v42
	v_and_b32_e32 v150, 31, v24
	s_add_u32 s34, s14, s20
	v_add_u32_e32 v0, s13, v25
	v_add_u32_e32 v2, s13, v67
	v_add_u32_e32 v50, 0x400, v24
	v_add_u32_e32 v60, 0x600, v24
	s_addc_u32 s35, s15, 0
	v_lshlrev_b32_e32 v160, 4, v150
	v_ashrrev_i32_e32 v1, 31, v0
	v_ashrrev_i32_e32 v3, 31, v2
	v_ashrrev_i32_e32 v70, 5, v50
	v_ashrrev_i32_e32 v71, 5, v60
	v_lshl_add_u64 v[26:27], s[34:35], 0, v[160:161]
	v_lshlrev_b64 v[0:1], 11, v[0:1]
	v_lshlrev_b64 v[2:3], 11, v[2:3]
	v_add_u32_e32 v8, s13, v70
	v_add_u32_e32 v10, s13, v71
	v_add_u32_e32 v16, 0x800, v24
	v_add_u32_e32 v18, 0xa00, v24
	v_lshl_add_u64 v[0:1], v[26:27], 0, v[0:1]
	v_lshl_add_u64 v[4:5], v[26:27], 0, v[2:3]
	v_ashrrev_i32_e32 v9, 31, v8
	v_ashrrev_i32_e32 v11, 31, v10
	v_ashrrev_i32_e32 v72, 5, v16
	v_ashrrev_i32_e32 v73, 5, v18
	global_load_dwordx4 v[0:3], v[0:1], off
	s_nop 0
	global_load_dwordx4 v[4:7], v[4:5], off
	v_lshlrev_b64 v[8:9], 11, v[8:9]
	v_lshlrev_b64 v[10:11], 11, v[10:11]
	v_add_u32_e32 v16, s13, v72
	v_add_u32_e32 v18, s13, v73
	v_add_u32_e32 v28, 0xc00, v24
	v_add_u32_e32 v30, 0xe00, v24
	v_lshl_add_u64 v[8:9], v[26:27], 0, v[8:9]
	v_lshl_add_u64 v[12:13], v[26:27], 0, v[10:11]
	v_ashrrev_i32_e32 v17, 31, v16
	v_ashrrev_i32_e32 v19, 31, v18
	v_ashrrev_i32_e32 v74, 5, v28
	v_ashrrev_i32_e32 v75, 5, v30
	global_load_dwordx4 v[8:11], v[8:9], off
	s_nop 0
	global_load_dwordx4 v[12:15], v[12:13], off
	v_lshlrev_b64 v[16:17], 11, v[16:17]
	v_lshlrev_b64 v[18:19], 11, v[18:19]
	v_add_u32_e32 v28, s13, v74
	v_add_u32_e32 v30, s13, v75
	v_lshl_add_u64 v[16:17], v[26:27], 0, v[16:17]
	v_lshl_add_u64 v[20:21], v[26:27], 0, v[18:19]
	v_ashrrev_i32_e32 v29, 31, v28
	v_ashrrev_i32_e32 v31, 31, v30
	s_add_u32 s34, s8, s12
	v_lshlrev_b32_e32 v34, 4, v24
	v_add_u32_e32 v66, 0, v160
	global_load_dwordx4 v[16:19], v[16:17], off
	s_nop 0
	global_load_dwordx4 v[20:23], v[20:21], off
	v_lshlrev_b64 v[28:29], 11, v[28:29]
	v_lshlrev_b64 v[30:31], 11, v[30:31]
	s_addc_u32 s35, s9, 0
	v_and_b32_e32 v160, 0xf0, v34
	v_ashrrev_i32_e32 v76, 4, v24
	v_lshl_add_u64 v[28:29], v[26:27], 0, v[28:29]
	v_lshl_add_u64 v[30:31], v[26:27], 0, v[30:31]
	v_lshl_add_u64 v[58:59], s[34:35], 0, v[160:161]
	s_add_u32 s34, s52, s12
	v_add_u32_e32 v34, s13, v76
	global_load_dwordx4 v[26:29], v[28:29], off
	s_nop 0
	global_load_dwordx4 v[30:33], v[30:31], off
	s_addc_u32 s35, s62, 0
	v_ashrrev_i32_e32 v35, 31, v34
	v_ashrrev_i32_e32 v77, 4, v42
	v_lshl_add_u64 v[62:63], s[34:35], 0, v[160:161]
	v_lshlrev_b64 v[34:35], 10, v[34:35]
	v_add_u32_e32 v42, s13, v77
	v_lshl_add_u64 v[36:37], v[58:59], 0, v[34:35]
	v_lshl_add_u64 v[38:39], v[62:63], 0, v[34:35]
	v_ashrrev_i32_e32 v43, 31, v42
	v_ashrrev_i32_e32 v78, 4, v50
	global_load_dwordx4 v[34:37], v[36:37], off
	s_nop 0
	global_load_dwordx4 v[38:41], v[38:39], off
	v_lshlrev_b64 v[42:43], 10, v[42:43]
	v_add_u32_e32 v50, s13, v78
	v_lshl_add_u64 v[44:45], v[58:59], 0, v[42:43]
	v_lshl_add_u64 v[46:47], v[62:63], 0, v[42:43]
	v_ashrrev_i32_e32 v51, 31, v50
	v_ashrrev_i32_e32 v79, 4, v60
	global_load_dwordx4 v[42:45], v[44:45], off
	s_nop 0
	global_load_dwordx4 v[46:49], v[46:47], off
	v_lshlrev_b64 v[50:51], 10, v[50:51]
	v_add_u32_e32 v60, s13, v79
	v_lshl_add_u64 v[52:53], v[58:59], 0, v[50:51]
	v_lshl_add_u64 v[54:55], v[62:63], 0, v[50:51]
	v_ashrrev_i32_e32 v61, 31, v60
	global_load_dwordx4 v[50:53], v[52:53], off
	s_nop 0
	global_load_dwordx4 v[54:57], v[54:55], off
	v_lshlrev_b64 v[64:65], 10, v[60:61]
	v_lshl_add_u64 v[58:59], v[58:59], 0, v[64:65]
	global_load_dwordx4 v[58:61], v[58:59], off
	v_lshl_add_u64 v[62:63], v[62:63], 0, v[64:65]
	global_load_dwordx4 v[62:65], v[62:63], off
	v_mad_u64_u32 v[68:69], s[34:35], v25, s54, v[66:67]
	s_add_i32 s20, 0, 0x1ac00
	v_bfe_u32 v146, v24, 5, 1
	v_lshrrev_b32_e32 v25, 2, v24
	s_movk_i32 s36, 0x4000
	s_movk_i32 s37, 0x6000
	s_movk_i32 s77, 0x60
	s_waitcnt vmcnt(15)
	ds_write_b128 v68, v[0:3]
	v_mad_u64_u32 v[0:1], s[34:35], v67, s54, v[66:67]
	s_waitcnt vmcnt(14)
	ds_write_b128 v0, v[4:7]
	v_mad_u64_u32 v[0:1], s[34:35], v70, s54, v[66:67]
	v_lshrrev_b32_e32 v4, 1, v24
	s_waitcnt vmcnt(13)
	ds_write_b128 v0, v[8:11]
	v_mad_u64_u32 v[0:1], s[34:35], v71, s54, v[66:67]
	s_waitcnt vmcnt(12)
	ds_write_b128 v0, v[12:15]
	v_mad_u64_u32 v[0:1], s[34:35], v72, s54, v[66:67]
	s_waitcnt vmcnt(11)
	ds_write_b128 v0, v[16:19]
	v_mad_u64_u32 v[0:1], s[34:35], v73, s54, v[66:67]
	s_waitcnt vmcnt(10)
	ds_write_b128 v0, v[20:23]
	v_mad_u64_u32 v[0:1], s[34:35], v74, s54, v[66:67]
	s_waitcnt vmcnt(9)
	ds_write_b128 v0, v[26:29]
	v_mad_u64_u32 v[0:1], s[34:35], v75, s54, v[66:67]
	v_readlane_b32 s35, v255, 49
	s_movk_i32 s34, 0x110
	s_waitcnt vmcnt(8)
	ds_write_b128 v0, v[30:33]
	v_add_u32_e32 v0, s35, v160
	v_add_u32_e32 v1, s20, v160
	v_mul_lo_u32 v2, v76, s34
	v_add_u32_e32 v3, v0, v2
	v_add_u32_e32 v2, v1, v2
	s_waitcnt vmcnt(7)
	ds_write_b128 v3, v[34:37]
	s_waitcnt vmcnt(6)
	ds_write_b128 v2, v[38:41]
	v_mul_lo_u32 v2, v77, s34
	v_add_u32_e32 v3, v0, v2
	v_add_u32_e32 v2, v1, v2
	v_lshlrev_b32_e32 v160, 4, v146
	s_waitcnt vmcnt(5)
	ds_write_b128 v3, v[42:45]
	s_waitcnt vmcnt(4)
	ds_write_b128 v2, v[46:49]
	v_mul_lo_u32 v2, v78, s34
	v_add_u32_e32 v3, v0, v2
	v_add_u32_e32 v2, v1, v2
	s_waitcnt vmcnt(3)
	ds_write_b128 v3, v[50:53]
	s_waitcnt vmcnt(2)
	ds_write_b128 v2, v[54:57]
	v_mul_lo_u32 v2, v79, s34
	v_add_u32_e32 v0, v0, v2
	s_waitcnt vmcnt(1)
	ds_write_b128 v0, v[58:61]
	v_add_u32_e32 v0, v1, v2
	s_waitcnt vmcnt(0)
	ds_write_b128 v0, v[62:65]
	v_mul_u32_u24_e32 v0, 0x110, v150
	v_add3_u32 v27, s20, v160, v0
	s_waitcnt lgkmcnt(0)
	s_barrier
; #define LAS __attribute__((address_space(3)))
; __device__ __forceinline__ unsigned cvt_pk_bf16(float lo, float hi) { f32x2 v = {lo, hi}; bf16x2_t b = __builtin_convertvector(v, bf16x2_t); return __builtin_bit_cast(unsigned, b); }
; __device__ __forceinline__ f32x16 mfma32(bf16x8 a, bf16x8 b, f32x16 c) { return __builtin_amdgcn_mfma_f32_32x32x16_bf16(a, b, c, 0, 0, 0); }
; __device__ void ret_out_item(const bf16_t* __restrict__ Qb, const bf16_t* __restrict__ Kb, bf16_t* Vb, const bf16_t* __restrict__ STf, const bf16_t* __restrict__ STb,
;                              int cidx, int head, float lgf2, float lgb2, LAS unsigned char* lds) {
;     ...
;   const int ib = w & 3, eh = w >> 2, il = l & 31, h = l >> 5;
;   const int i16 = l & 15, q4 = i16 >> 2, p4 = i16 & 3, G1 = (l >> 4) & 1;
;   const int iloc = ib * 32 + il;
;   bf16x8 qf[8];
; #pragma unroll
;   for (int ks = 0; ks < 8; ++ks) qf[ks] = *(const LAS bf16x8*)(lds + OQ + iloc * QS + (16 * ks + 8 * h) * 2);
;   bf16x8 pf[4][2];
; #pragma unroll
;   for (int jt = 0; jt < 4; ++jt) {
;     f32x16 a = {};
; #pragma unroll
;     for (int ks = 0; ks < 8; ++ks) a = mfma32(*(const LAS bf16x8*)(lds + OK + (jt * 32 + il) * QS + (16 * ks + 8 * h) * 2), qf[ks], a);
;     u32x4 p0, p1;
; #pragma unroll
;     for (int r = 0; r < 16; r += 2) {
;       float v[2];
; #pragma unroll
;       for (int e = 0; e < 2; ++e) { const int jl = jt * 32 + ((r + e) & 3) + 8 * ((r + e) >> 2) + 4 * h; const int dd = iloc - jl;
;         const float dec = dd >= 0 ? __builtin_amdgcn_exp2f(lgf2 * (float)dd) : __builtin_amdgcn_exp2f(lgb2 * (float)(-dd)); v[e] = a[r + e] * dec; }
;       const unsigned pk = cvt_pk_bf16(v[0], v[1]);
;       if (r < 8) p0[r >> 1] = pk; else p1[(r - 8) >> 1] = pk;
;     }
;     pf[jt][0] = (bf16x8)p0; pf[jt][1] = (bf16x8)p1;
	s_and_b32 s38, s101, 0xc0
	s_cmp_eq_u32 s38, 0
	s_cbranch_scc0 .Lropf_skip
	v_ashrrev_i32_e32 v206, 1, v214
	v_and_b32_e32 v206, 0xffffff80, v206
	v_and_b32_e32 v207, 31, v214
	v_or_b32_e32 v206, v206, v207
	v_mov_b32_e32 v207, 0
	v_lshl_add_u64 v[206:207], s[22:23], 0, v[206:207]
	v_lshlrev_b64 v[206:207], 8, v[206:207]
	v_readlane_b32 s38, v250, 51
	v_readlane_b32 s39, v250, 52
	v_lshl_add_u64 v[208:209], s[38:39], 0, v[206:207]
	s_mov_b32 s38, 0x2000
	s_mov_b32 s39, 0
	global_load_dword v210, v[208:209], off
	global_load_dword v210, v[208:209], off offset:128
	v_lshl_add_u64 v[208:209], v[208:209], 0, s[38:39]
	global_load_dword v210, v[208:209], off
	global_load_dword v210, v[208:209], off offset:128
	v_lshl_add_u64 v[208:209], v[208:209], 0, s[38:39]
	global_load_dword v210, v[208:209], off
	global_load_dword v210, v[208:209], off offset:128
	v_lshl_add_u64 v[208:209], v[208:209], 0, s[38:39]
	global_load_dword v210, v[208:209], off
	global_load_dword v210, v[208:209], off offset:128
	v_readlane_b32 s38, v250, 53
	v_readlane_b32 s39, v250, 54
	v_lshl_add_u64 v[208:209], s[38:39], 0, v[206:207]
	s_mov_b32 s38, 0x2000
	s_mov_b32 s39, 0
	global_load_dword v210, v[208:209], off
	global_load_dword v210, v[208:209], off offset:128
	v_lshl_add_u64 v[208:209], v[208:209], 0, s[38:39]
	global_load_dword v210, v[208:209], off
	global_load_dword v210, v[208:209], off offset:128
	v_lshl_add_u64 v[208:209], v[208:209], 0, s[38:39]
	global_load_dword v210, v[208:209], off
	global_load_dword v210, v[208:209], off offset:128
	v_lshl_add_u64 v[208:209], v[208:209], 0, s[38:39]
	global_load_dword v210, v[208:209], off
	global_load_dword v210, v[208:209], off offset:128
.Lropf_skip:
	ds_read_b128 v[0:3], v27
	s_movk_i32 s34, 0x60
	v_and_or_b32 v147, v4, s34, v150
	v_mul_u32_u24_e32 v4, 0x110, v147
	v_add3_u32 v26, s35, v4, v160
	ds_read_b128 v[108:111], v26
	ds_read_b128 v[104:107], v26 offset:32
	ds_read_b128 v[4:7], v27 offset:32
	s_waitcnt lgkmcnt(2)
	v_mfma_f32_32x32x16_bf16 v[8:23], v[0:3], v[108:111], 0
	s_movk_i32 s20, 0x41
	s_waitcnt lgkmcnt(0)
	v_mfma_f32_32x32x16_bf16 v[8:23], v[4:7], v[104:107], v[8:23]
	ds_read_b128 v[0:3], v27 offset:64
	ds_read_b128 v[100:103], v26 offset:64
	ds_read_b128 v[96:99], v26 offset:96
	ds_read_b128 v[4:7], v27 offset:96
	s_waitcnt lgkmcnt(2)
	v_mfma_f32_32x32x16_bf16 v[8:23], v[0:3], v[100:103], v[8:23]
	s_waitcnt lgkmcnt(0)
	v_mfma_f32_32x32x16_bf16 v[8:23], v[4:7], v[96:99], v[8:23]
	ds_read_b128 v[0:3], v27 offset:128
	ds_read_b128 v[92:95], v26 offset:128
	ds_read_b128 v[88:91], v26 offset:160
	ds_read_b128 v[4:7], v27 offset:160
	s_waitcnt lgkmcnt(2)
	v_mfma_f32_32x32x16_bf16 v[8:23], v[0:3], v[92:95], v[8:23]
	ds_read_b128 v[0:3], v27 offset:192
	ds_read_b128 v[84:87], v26 offset:192
	ds_read_b128 v[80:83], v26 offset:224
	v_lshlrev_b32_e32 v26, 2, v146
	v_sub_u32_e32 v137, v147, v26
	v_cmp_gt_i32_e32 vcc, 0, v137
	ds_read_b128 v[28:31], v27 offset:8736
	v_subrev_u32_e32 v36, 26, v137
	s_waitcnt lgkmcnt(4)
	v_mfma_f32_32x32x16_bf16 v[8:23], v[4:7], v[88:91], v[8:23]
	ds_read_b128 v[4:7], v27 offset:224
	v_sub_u32_e32 v37, 26, v137
	v_subrev_u32_e32 v38, 27, v137
	v_sub_u32_e32 v39, 27, v137
	s_waitcnt lgkmcnt(2)
	v_lshlrev_b32_e32 v202, 16, v82
	v_and_b32_e32 v203, 0xffff0000, v82
	v_lshlrev_b32_e32 v204, 16, v83
	v_mfma_f32_32x32x16_bf16 v[8:23], v[0:3], v[84:87], v[8:23]
	v_sub_u32_e32 v0, 0, v137
	v_max_i32_e32 v0, v137, v0
	v_cndmask_b32_e32 v1, v149, v148, vcc
	v_add_u32_e32 v2, -1, v137
	v_sub_u32_e32 v3, 1, v137
	v_cmp_lt_i32_e32 vcc, 0, v137
	v_cvt_f32_u32_e32 v0, v0
	s_waitcnt lgkmcnt(0)
	v_mfma_f32_32x32x16_bf16 v[8:23], v[4:7], v[80:83], v[8:23]
	v_cndmask_b32_e32 v2, v3, v2, vcc
	v_cvt_f32_u32_e32 v2, v2
	v_mul_f32_e32 v0, v1, v0
	v_cndmask_b32_e32 v1, v148, v149, vcc
	v_sub_u32_e32 v3, 2, v137
	v_mul_f32_e32 v1, v1, v2
	v_add_u32_e32 v2, -2, v137
	v_cmp_lt_i32_e32 vcc, 1, v137
	v_add_u32_e32 v4, -3, v137
	v_sub_u32_e32 v5, 3, v137
	v_cndmask_b32_e32 v2, v3, v2, vcc
	v_cndmask_b32_e32 v3, v148, v149, vcc
	v_cmp_lt_i32_e32 vcc, 2, v137
	v_cvt_f32_u32_e32 v2, v2
	v_add_u32_e32 v6, -9, v137
	v_cndmask_b32_e32 v4, v5, v4, vcc
	v_cvt_f32_u32_e32 v4, v4
	v_mul_f32_e32 v2, v3, v2
	v_cndmask_b32_e32 v3, v148, v149, vcc
	v_sub_u32_e32 v5, 8, v137
	v_mul_f32_e32 v3, v3, v4
	v_add_u32_e32 v4, -8, v137
	v_cmp_lt_i32_e32 vcc, 7, v137
	v_sub_u32_e32 v7, 9, v137
	v_exp_f32_e32 v0, v0
	v_cndmask_b32_e32 v4, v5, v4, vcc
	v_cndmask_b32_e32 v5, v148, v149, vcc
	v_cmp_lt_i32_e32 vcc, 8, v137
	v_cvt_f32_u32_e32 v4, v4
	v_exp_f32_e32 v1, v1
	v_cndmask_b32_e32 v6, v7, v6, vcc
	v_cvt_f32_u32_e32 v6, v6
	v_mul_f32_e32 v4, v5, v4
	v_cndmask_b32_e32 v5, v148, v149, vcc
	v_exp_f32_e32 v2, v2
	v_exp_f32_e32 v3, v3
	v_mul_f32_e32 v5, v5, v6
	v_exp_f32_e32 v4, v4
	v_exp_f32_e32 v5, v5
	v_pk_mul_f32 v[0:1], v[0:1], v[8:9]
	v_cmp_lt_i32_e32 vcc, 9, v137
	v_cvt_pk_bf16_f32 v112, v0, v1
	v_pk_mul_f32 v[0:1], v[2:3], v[10:11]
	v_add_u32_e32 v2, -10, v137
	v_sub_u32_e32 v3, 10, v137
	v_cvt_pk_bf16_f32 v113, v0, v1
	v_pk_mul_f32 v[0:1], v[4:5], v[12:13]
	v_cndmask_b32_e32 v2, v3, v2, vcc
	v_cndmask_b32_e32 v3, v148, v149, vcc
	v_add_u32_e32 v4, -11, v137
	v_sub_u32_e32 v5, 11, v137
	v_cmp_lt_i32_e32 vcc, 10, v137
	v_cvt_f32_u32_e32 v2, v2
	v_cvt_pk_bf16_f32 v114, v0, v1
	v_cndmask_b32_e32 v4, v5, v4, vcc
	v_cvt_f32_u32_e32 v4, v4
	v_mul_f32_e32 v2, v3, v2
	v_cndmask_b32_e32 v3, v148, v149, vcc
	v_sub_u32_e32 v5, 16, v137
	v_mul_f32_e32 v3, v3, v4
	v_add_u32_e32 v4, -16, v137
	v_cmp_lt_i32_e32 vcc, 15, v137
	v_exp_f32_e32 v2, v2
	v_exp_f32_e32 v3, v3
	v_cndmask_b32_e32 v4, v5, v4, vcc
	v_cvt_f32_u32_e32 v6, v4
	v_cndmask_b32_e32 v0, v148, v149, vcc
	v_sub_u32_e32 v1, 17, v137
	v_cmp_lt_i32_e32 vcc, 16, v137
	v_mul_f32_e32 v0, v0, v6
	v_exp_f32_e32 v6, v0
	v_subrev_u32_e32 v0, 17, v137
	v_cndmask_b32_e32 v0, v1, v0, vcc
	v_pk_mul_f32 v[4:5], v[2:3], v[14:15]
	v_cndmask_b32_e32 v1, v148, v149, vcc
	v_cvt_f32_u32_e32 v0, v0
	v_subrev_u32_e32 v2, 18, v137
	v_sub_u32_e32 v3, 18, v137
	v_cmp_lt_i32_e32 vcc, 17, v137
	v_mul_f32_e32 v0, v1, v0
	v_exp_f32_e32 v7, v0
	v_cndmask_b32_e32 v2, v3, v2, vcc
	v_cvt_f32_u32_e32 v2, v2
	v_cndmask_b32_e32 v0, v148, v149, vcc
	v_subrev_u32_e32 v1, 19, v137
	v_cmp_lt_i32_e32 vcc, 18, v137
	v_mul_f32_e32 v0, v0, v2
	v_sub_u32_e32 v2, 19, v137
	v_cndmask_b32_e32 v1, v2, v1, vcc
	v_cvt_f32_u32_e32 v9, v1
	v_exp_f32_e32 v8, v0
	ds_read_b128 v[0:3], v27 offset:8704
	v_cndmask_b32_e32 v10, v148, v149, vcc
	v_mul_f32_e32 v9, v10, v9
	v_exp_f32_e32 v9, v9
	v_cvt_pk_bf16_f32 v115, v4, v5
	v_pk_mul_f32 v[4:5], v[6:7], v[16:17]
	v_cmp_lt_i32_e32 vcc, 23, v137
	v_cvt_pk_bf16_f32 v116, v4, v5
	v_pk_mul_f32 v[32:33], v[8:9], v[18:19]
	s_waitcnt lgkmcnt(0)
; #define LAS __attribute__((address_space(3)))
; __device__ __forceinline__ unsigned cvt_pk_bf16(float lo, float hi) { f32x2 v = {lo, hi}; bf16x2_t b = __builtin_convertvector(v, bf16x2_t); return __builtin_bit_cast(unsigned, b); }
; __device__ __forceinline__ f32x16 mfma32(bf16x8 a, bf16x8 b, f32x16 c) { return __builtin_amdgcn_mfma_f32_32x32x16_bf16(a, b, c, 0, 0, 0); }
; __device__ void ret_out_item(const bf16_t* __restrict__ Qb, const bf16_t* __restrict__ Kb, bf16_t* Vb, const bf16_t* __restrict__ STf, const bf16_t* __restrict__ STb,
;                              int cidx, int head, float lgf2, float lgb2, LAS unsigned char* lds) {
;     ...
;   for (int jt = 0; jt < 4; ++jt) {
;     f32x16 a = {};
; #pragma unroll
;     for (int ks = 0; ks < 8; ++ks) a = mfma32(*(const LAS bf16x8*)(lds + OK + (jt * 32 + il) * QS + (16 * ks + 8 * h) * 2), qf[ks], a);
;     u32x4 p0, p1;
; #pragma unroll
;     for (int r = 0; r < 16; r += 2) {
;       float v[2];
; #pragma unroll
;       for (int e = 0; e < 2; ++e) { const int jl = jt * 32 + ((r + e) & 3) + 8 * ((r + e) >> 2) + 4 * h; const int dd = iloc - jl;
;         const float dec = dd >= 0 ? __builtin_amdgcn_exp2f(lgf2 * (float)dd) : __builtin_amdgcn_exp2f(lgb2 * (float)(-dd)); v[e] = a[r + e] * dec; }
;       const unsigned pk = cvt_pk_bf16(v[0], v[1]);
;       if (r < 8) p0[r >> 1] = pk; else p1[(r - 8) >> 1] = pk;
;     }
;     pf[jt][0] = (bf16x8)p0; pf[jt][1] = (bf16x8)p1;
	v_mfma_f32_32x32x16_bf16 v[4:19], v[0:3], v[108:111], 0
	v_subrev_u32_e32 v0, 24, v137
	v_sub_u32_e32 v1, 24, v137
	v_cndmask_b32_e32 v0, v1, v0, vcc
	v_cvt_f32_u32_e32 v34, v0
	ds_read_b128 v[0:3], v27 offset:8768
	v_cndmask_b32_e32 v35, v148, v149, vcc
	v_cmp_lt_i32_e32 vcc, 24, v137
	v_mfma_f32_32x32x16_bf16 v[4:19], v[28:31], v[104:107], v[4:19]
	v_subrev_u32_e32 v28, 25, v137
	v_sub_u32_e32 v29, 25, v137
	v_cndmask_b32_e32 v28, v29, v28, vcc
	v_mul_f32_e32 v34, v35, v34
	v_cvt_f32_u32_e32 v35, v28
	ds_read_b128 v[28:31], v27 offset:8800
	v_exp_f32_e32 v34, v34
	s_waitcnt lgkmcnt(1)
	v_mfma_f32_32x32x16_bf16 v[4:19], v[0:3], v[100:103], v[4:19]
	v_cndmask_b32_e32 v0, v148, v149, vcc
	v_mul_f32_e32 v0, v0, v35
	v_exp_f32_e32 v35, v0
	ds_read_b128 v[0:3], v27 offset:8832
	v_cmp_lt_i32_e32 vcc, 25, v137
	v_cvt_pk_bf16_f32 v117, v32, v33
	v_pk_mul_f32 v[20:21], v[34:35], v[20:21]
	s_waitcnt lgkmcnt(1)
	v_mfma_f32_32x32x16_bf16 v[4:19], v[28:31], v[96:99], v[4:19]
	v_cndmask_b32_e32 v28, v37, v36, vcc
	v_cvt_f32_u32_e32 v37, v28
	ds_read_b128 v[28:31], v27 offset:8864
	v_cndmask_b32_e32 v36, v148, v149, vcc
	v_cmp_lt_i32_e32 vcc, 26, v137
	v_cvt_pk_bf16_f32 v118, v20, v21
	v_and_b32_e32 v205, 0xffff0000, v83
	s_waitcnt lgkmcnt(1)
	v_mfma_f32_32x32x16_bf16 v[4:19], v[0:3], v[92:95], v[4:19]
	v_cndmask_b32_e32 v0, v39, v38, vcc
	v_cvt_f32_u32_e32 v0, v0
	v_mul_f32_e32 v1, v36, v37
	v_exp_f32_e32 v36, v1
	v_cndmask_b32_e32 v1, v148, v149, vcc
	v_mul_f32_e32 v37, v1, v0
	ds_read_b128 v[0:3], v27 offset:8896
	s_waitcnt lgkmcnt(1)
	v_mfma_f32_32x32x16_bf16 v[4:19], v[28:31], v[88:91], v[4:19]
	v_exp_f32_e32 v37, v37
	v_cmp_lt_i32_e32 vcc, 31, v137
	v_subrev_u32_e32 v28, 56, v137
	v_sub_u32_e32 v29, 56, v137
	v_pk_mul_f32 v[20:21], v[36:37], v[22:23]
	v_subrev_u32_e32 v36, 58, v137
	v_cvt_pk_bf16_f32 v119, v20, v21
	ds_read_b128 v[20:23], v27 offset:8928
	s_waitcnt lgkmcnt(1)
	v_mfma_f32_32x32x16_bf16 v[4:19], v[0:3], v[84:87], v[4:19]
	v_subrev_u32_e32 v0, 32, v137
	v_sub_u32_e32 v1, 32, v137
	v_cndmask_b32_e32 v0, v1, v0, vcc
	v_cndmask_b32_e32 v1, v148, v149, vcc
	v_subrev_u32_e32 v2, 33, v137
	v_sub_u32_e32 v3, 33, v137
	v_cmp_lt_i32_e32 vcc, 32, v137
	v_cvt_f32_u32_e32 v0, v0
	s_waitcnt lgkmcnt(0)
	v_mfma_f32_32x32x16_bf16 v[4:19], v[20:23], v[80:83], v[4:19]
	v_cndmask_b32_e32 v2, v3, v2, vcc
	v_cvt_f32_u32_e32 v2, v2
	v_mul_f32_e32 v0, v1, v0
	v_cndmask_b32_e32 v1, v148, v149, vcc
	v_exp_f32_e32 v0, v0
	v_mul_f32_e32 v1, v1, v2
	v_exp_f32_e32 v1, v1
	v_subrev_u32_e32 v2, 34, v137
	v_sub_u32_e32 v3, 34, v137
	v_cmp_lt_i32_e32 vcc, 33, v137
	s_nop 1
	v_pk_mul_f32 v[0:1], v[0:1], v[4:5]
	v_subrev_u32_e32 v4, 35, v137
	v_cndmask_b32_e32 v2, v3, v2, vcc
	v_cndmask_b32_e32 v3, v148, v149, vcc
	v_sub_u32_e32 v5, 35, v137
	v_cmp_lt_i32_e32 vcc, 34, v137
	v_cvt_f32_u32_e32 v2, v2
	v_subrev_u32_e32 v20, 41, v137
	v_cndmask_b32_e32 v4, v5, v4, vcc
	v_cvt_f32_u32_e32 v4, v4
	v_mul_f32_e32 v2, v3, v2
	v_cndmask_b32_e32 v3, v148, v149, vcc
	v_sub_u32_e32 v5, 40, v137
	v_mul_f32_e32 v3, v3, v4
	v_subrev_u32_e32 v4, 40, v137
	v_cmp_lt_i32_e32 vcc, 39, v137
	v_sub_u32_e32 v21, 41, v137
	v_exp_f32_e32 v2, v2
	v_cndmask_b32_e32 v4, v5, v4, vcc
	v_cndmask_b32_e32 v5, v148, v149, vcc
	v_cmp_lt_i32_e32 vcc, 40, v137
	v_cvt_f32_u32_e32 v4, v4
	v_exp_f32_e32 v3, v3
	v_cndmask_b32_e32 v20, v21, v20, vcc
	v_cvt_f32_u32_e32 v20, v20
	v_mul_f32_e32 v4, v5, v4
	v_cndmask_b32_e32 v5, v148, v149, vcc
	v_exp_f32_e32 v4, v4
	v_mul_f32_e32 v5, v5, v20
	v_exp_f32_e32 v5, v5
	v_cvt_pk_bf16_f32 v120, v0, v1
	v_pk_mul_f32 v[0:1], v[2:3], v[6:7]
	v_subrev_u32_e32 v2, 42, v137
	v_sub_u32_e32 v3, 42, v137
	v_cmp_lt_i32_e32 vcc, 41, v137
	v_cvt_pk_bf16_f32 v121, v0, v1
	v_pk_mul_f32 v[0:1], v[4:5], v[8:9]
	v_cndmask_b32_e32 v2, v3, v2, vcc
	v_cndmask_b32_e32 v3, v148, v149, vcc
	v_subrev_u32_e32 v4, 43, v137
	v_sub_u32_e32 v5, 43, v137
	v_cmp_lt_i32_e32 vcc, 42, v137
	v_cvt_f32_u32_e32 v2, v2
	v_cvt_pk_bf16_f32 v122, v0, v1
	v_cndmask_b32_e32 v4, v5, v4, vcc
	v_cvt_f32_u32_e32 v4, v4
	v_mul_f32_e32 v2, v3, v2
	v_cndmask_b32_e32 v3, v148, v149, vcc
	v_sub_u32_e32 v5, 48, v137
	v_mul_f32_e32 v3, v3, v4
	v_subrev_u32_e32 v4, 48, v137
	v_cmp_lt_i32_e32 vcc, 47, v137
	v_exp_f32_e32 v2, v2
	v_exp_f32_e32 v3, v3
	v_cndmask_b32_e32 v4, v5, v4, vcc
	v_cvt_f32_u32_e32 v6, v4
	v_cndmask_b32_e32 v0, v148, v149, vcc
	v_sub_u32_e32 v1, 49, v137
	v_cmp_lt_i32_e32 vcc, 48, v137
	v_mul_f32_e32 v0, v0, v6
	v_exp_f32_e32 v6, v0
	v_subrev_u32_e32 v0, 49, v137
	v_cndmask_b32_e32 v0, v1, v0, vcc
	v_pk_mul_f32 v[4:5], v[2:3], v[10:11]
	v_cndmask_b32_e32 v1, v148, v149, vcc
	v_cvt_f32_u32_e32 v0, v0
	v_subrev_u32_e32 v2, 50, v137
	v_sub_u32_e32 v3, 50, v137
	v_cmp_lt_i32_e32 vcc, 49, v137
	v_mul_f32_e32 v0, v1, v0
	v_exp_f32_e32 v7, v0
	v_cndmask_b32_e32 v2, v3, v2, vcc
	v_cvt_f32_u32_e32 v2, v2
	v_cndmask_b32_e32 v0, v148, v149, vcc
	v_subrev_u32_e32 v1, 51, v137
	v_cmp_lt_i32_e32 vcc, 50, v137
	v_mul_f32_e32 v0, v0, v2
	v_sub_u32_e32 v2, 51, v137
	v_cndmask_b32_e32 v1, v2, v1, vcc
	v_cvt_f32_u32_e32 v9, v1
	v_exp_f32_e32 v8, v0
	ds_read_b128 v[0:3], v27 offset:17408
	ds_read_b128 v[20:23], v27 offset:17440
	v_cndmask_b32_e32 v10, v148, v149, vcc
	v_mul_f32_e32 v9, v10, v9
	v_exp_f32_e32 v9, v9
	v_cvt_pk_bf16_f32 v123, v4, v5
	v_pk_mul_f32 v[4:5], v[6:7], v[12:13]
	v_cmp_lt_i32_e32 vcc, 55, v137
	v_cvt_pk_bf16_f32 v124, v4, v5
	v_pk_mul_f32 v[32:33], v[8:9], v[14:15]
	s_waitcnt lgkmcnt(1)
	v_mfma_f32_32x32x16_bf16 v[0:15], v[0:3], v[108:111], 0
	v_cndmask_b32_e32 v28, v29, v28, vcc
	v_cvt_f32_u32_e32 v34, v28
	ds_read_b128 v[28:31], v27 offset:17472
	v_cndmask_b32_e32 v35, v148, v149, vcc
	v_cmp_lt_i32_e32 vcc, 56, v137
	v_mul_f32_e32 v34, v35, v34
	v_sub_u32_e32 v37, 58, v137
	s_waitcnt lgkmcnt(1)
; #define LAS __attribute__((address_space(3)))
; __device__ __forceinline__ unsigned cvt_pk_bf16(float lo, float hi) { f32x2 v = {lo, hi}; bf16x2_t b = __builtin_convertvector(v, bf16x2_t); return __builtin_bit_cast(unsigned, b); }
; __device__ __forceinline__ f32x16 mfma32(bf16x8 a, bf16x8 b, f32x16 c) { return __builtin_amdgcn_mfma_f32_32x32x16_bf16(a, b, c, 0, 0, 0); }
; __device__ void ret_out_item(const bf16_t* __restrict__ Qb, const bf16_t* __restrict__ Kb, bf16_t* Vb, const bf16_t* __restrict__ STf, const bf16_t* __restrict__ STb,
;                              int cidx, int head, float lgf2, float lgb2, LAS unsigned char* lds) {
;     ...
;   for (int jt = 0; jt < 4; ++jt) {
;     f32x16 a = {};
; #pragma unroll
;     for (int ks = 0; ks < 8; ++ks) a = mfma32(*(const LAS bf16x8*)(lds + OK + (jt * 32 + il) * QS + (16 * ks + 8 * h) * 2), qf[ks], a);
;     u32x4 p0, p1;
; #pragma unroll
;     for (int r = 0; r < 16; r += 2) {
;       float v[2];
; #pragma unroll
;       for (int e = 0; e < 2; ++e) { const int jl = jt * 32 + ((r + e) & 3) + 8 * ((r + e) >> 2) + 4 * h; const int dd = iloc - jl;
;         const float dec = dd >= 0 ? __builtin_amdgcn_exp2f(lgf2 * (float)dd) : __builtin_amdgcn_exp2f(lgb2 * (float)(-dd)); v[e] = a[r + e] * dec; }
;       const unsigned pk = cvt_pk_bf16(v[0], v[1]);
;       if (r < 8) p0[r >> 1] = pk; else p1[(r - 8) >> 1] = pk;
;     }
;     pf[jt][0] = (bf16x8)p0; pf[jt][1] = (bf16x8)p1;
	v_mfma_f32_32x32x16_bf16 v[0:15], v[20:23], v[104:107], v[0:15]
	v_subrev_u32_e32 v20, 57, v137
	v_sub_u32_e32 v21, 57, v137
	v_cndmask_b32_e32 v20, v21, v20, vcc
	v_cvt_f32_u32_e32 v35, v20
	ds_read_b128 v[20:23], v27 offset:17504
	v_subrev_u32_e32 v38, 59, v137
	v_sub_u32_e32 v39, 59, v137
	s_waitcnt lgkmcnt(1)
	v_mfma_f32_32x32x16_bf16 v[0:15], v[28:31], v[100:103], v[0:15]
	v_cndmask_b32_e32 v28, v148, v149, vcc
	v_mul_f32_e32 v28, v28, v35
	v_exp_f32_e32 v35, v28
	ds_read_b128 v[28:31], v27 offset:17536
	v_cmp_lt_i32_e32 vcc, 57, v137
	v_exp_f32_e32 v34, v34
	v_cvt_pk_bf16_f32 v125, v32, v33
	s_waitcnt lgkmcnt(1)
	v_mfma_f32_32x32x16_bf16 v[0:15], v[20:23], v[96:99], v[0:15]
	v_cndmask_b32_e32 v20, v37, v36, vcc
	v_cvt_f32_u32_e32 v37, v20
	ds_read_b128 v[20:23], v27 offset:17568
	v_cndmask_b32_e32 v36, v148, v149, vcc
	v_cmp_lt_i32_e32 vcc, 58, v137
	v_pk_mul_f32 v[16:17], v[34:35], v[16:17]
	s_waitcnt lgkmcnt(1)
	v_mfma_f32_32x32x16_bf16 v[0:15], v[28:31], v[92:95], v[0:15]
	v_cndmask_b32_e32 v28, v39, v38, vcc
	v_cvt_f32_u32_e32 v28, v28
	v_mul_f32_e32 v29, v36, v37
	v_exp_f32_e32 v36, v29
	v_cndmask_b32_e32 v29, v148, v149, vcc
	v_mul_f32_e32 v37, v29, v28
	ds_read_b128 v[28:31], v27 offset:17600
	s_waitcnt lgkmcnt(1)
	v_mfma_f32_32x32x16_bf16 v[0:15], v[20:23], v[88:91], v[0:15]
	v_exp_f32_e32 v37, v37
	v_cvt_pk_bf16_f32 v126, v16, v17
	v_subrev_u32_e32 v20, 64, v137
	v_sub_u32_e32 v21, 64, v137
	v_pk_mul_f32 v[16:17], v[36:37], v[18:19]
	v_cmp_lt_i32_e32 vcc, 63, v137
	v_cvt_pk_bf16_f32 v127, v16, v17
	ds_read_b128 v[16:19], v27 offset:17632
	s_waitcnt lgkmcnt(1)
	v_mfma_f32_32x32x16_bf16 v[0:15], v[28:31], v[84:87], v[0:15]
	v_cndmask_b32_e32 v20, v21, v20, vcc
	v_cvt_f32_u32_e32 v20, v20
	v_cndmask_b32_e32 v21, v148, v149, vcc
	v_add_u32_e32 v22, 0xffffffbf, v137
	v_sub_u32_e32 v23, 0x41, v137
	v_cmp_lt_i32_e32 vcc, 64, v137
	v_mul_f32_e32 v20, v21, v20
	s_waitcnt lgkmcnt(0)
	v_mfma_f32_32x32x16_bf16 v[0:15], v[16:19], v[80:83], v[0:15]
	v_cndmask_b32_e32 v22, v23, v22, vcc
	v_cvt_f32_u32_e32 v22, v22
	v_cndmask_b32_e32 v21, v148, v149, vcc
	v_add_u32_e32 v16, 0xffffffbe, v137
	v_sub_u32_e32 v17, 0x42, v137
	v_cmp_lt_i32_e32 vcc, s20, v137
	s_movk_i32 s20, 0x42
	v_add_u32_e32 v18, 0xffffffbd, v137
	v_cndmask_b32_e32 v16, v17, v16, vcc
	v_cndmask_b32_e32 v17, v148, v149, vcc
	v_sub_u32_e32 v19, 0x43, v137
	v_cmp_lt_i32_e32 vcc, s20, v137
	v_cvt_f32_u32_e32 v16, v16
	v_mul_f32_e32 v21, v21, v22
	v_cndmask_b32_e32 v18, v19, v18, vcc
	v_cvt_f32_u32_e32 v18, v18
	v_exp_f32_e32 v20, v20
	v_exp_f32_e32 v21, v21
	v_mul_f32_e32 v16, v17, v16
	v_cndmask_b32_e32 v17, v148, v149, vcc
	s_movk_i32 s20, 0x47
	v_mul_f32_e32 v17, v17, v18
	v_add_u32_e32 v18, 0xffffffb8, v137
	v_sub_u32_e32 v19, 0x48, v137
	v_cmp_lt_i32_e32 vcc, s20, v137
	s_movk_i32 s20, 0x48
	v_pk_mul_f32 v[0:1], v[20:21], v[0:1]
	v_cndmask_b32_e32 v18, v19, v18, vcc
	v_cndmask_b32_e32 v19, v148, v149, vcc
	v_add_u32_e32 v20, 0xffffffb7, v137
	v_sub_u32_e32 v21, 0x49, v137
	v_cmp_lt_i32_e32 vcc, s20, v137
	v_cvt_f32_u32_e32 v18, v18
	v_exp_f32_e32 v16, v16
	v_cndmask_b32_e32 v20, v21, v20, vcc
	v_cvt_f32_u32_e32 v20, v20
	v_mul_f32_e32 v18, v19, v18
	v_cndmask_b32_e32 v19, v148, v149, vcc
	v_exp_f32_e32 v17, v17
	v_mul_f32_e32 v19, v19, v20
	v_exp_f32_e32 v18, v18
	v_exp_f32_e32 v19, v19
	s_movk_i32 s20, 0x49
	v_cvt_pk_bf16_f32 v128, v0, v1
	v_pk_mul_f32 v[0:1], v[16:17], v[2:3]
	v_add_u32_e32 v2, 0xffffffb6, v137
	v_sub_u32_e32 v3, 0x4a, v137
	v_cmp_lt_i32_e32 vcc, s20, v137
	s_movk_i32 s20, 0x4a
	v_cvt_pk_bf16_f32 v129, v0, v1
	v_pk_mul_f32 v[0:1], v[18:19], v[4:5]
	v_cndmask_b32_e32 v2, v3, v2, vcc
	v_cndmask_b32_e32 v3, v148, v149, vcc
	v_add_u32_e32 v4, 0xffffffb5, v137
	v_sub_u32_e32 v5, 0x4b, v137
	v_cmp_lt_i32_e32 vcc, s20, v137
	v_cvt_f32_u32_e32 v2, v2
	s_movk_i32 s20, 0x4f
	v_cndmask_b32_e32 v4, v5, v4, vcc
	v_cvt_f32_u32_e32 v4, v4
	v_mul_f32_e32 v2, v3, v2
	v_cndmask_b32_e32 v3, v148, v149, vcc
	v_sub_u32_e32 v5, 0x50, v137
	v_mul_f32_e32 v3, v3, v4
	v_add_u32_e32 v4, 0xffffffb0, v137
	v_cmp_lt_i32_e32 vcc, s20, v137
	v_exp_f32_e32 v2, v2
	v_exp_f32_e32 v3, v3
	v_cndmask_b32_e32 v4, v5, v4, vcc
	v_cvt_f32_u32_e32 v4, v4
	v_cvt_pk_bf16_f32 v130, v0, v1
	v_cndmask_b32_e32 v0, v148, v149, vcc
	s_movk_i32 s20, 0x50
	v_mul_f32_e32 v0, v0, v4
	v_exp_f32_e32 v18, v0
	v_add_u32_e32 v0, 0xffffffaf, v137
	v_sub_u32_e32 v1, 0x51, v137
	v_cmp_lt_i32_e32 vcc, s20, v137
	s_movk_i32 s20, 0x51
	v_pk_mul_f32 v[16:17], v[2:3], v[6:7]
	v_cndmask_b32_e32 v0, v1, v0, vcc
	v_cndmask_b32_e32 v1, v148, v149, vcc
	v_cvt_f32_u32_e32 v0, v0
	v_add_u32_e32 v2, 0xffffffae, v137
	v_sub_u32_e32 v3, 0x52, v137
	v_cmp_lt_i32_e32 vcc, s20, v137
	v_mul_f32_e32 v0, v1, v0
	v_exp_f32_e32 v19, v0
	v_cndmask_b32_e32 v2, v3, v2, vcc
	v_cvt_f32_u32_e32 v2, v2
	v_cndmask_b32_e32 v0, v148, v149, vcc
	s_movk_i32 s20, 0x52
	v_sub_u32_e32 v5, 0x53, v137
	v_mul_f32_e32 v4, v0, v2
	ds_read_b128 v[0:3], v27 offset:26112
	v_exp_f32_e32 v20, v4
	v_add_u32_e32 v4, 0xffffffad, v137
	v_cmp_lt_i32_e32 vcc, s20, v137
	s_movk_i32 s20, 0x57
	v_cvt_pk_bf16_f32 v131, v16, v17
	v_cndmask_b32_e32 v4, v5, v4, vcc
	v_cvt_f32_u32_e32 v21, v4
	ds_read_b128 v[4:7], v27 offset:26144
	s_waitcnt lgkmcnt(1)
	v_mfma_f32_32x32x16_bf16 v[64:79], v[0:3], v[108:111], 0
	v_cndmask_b32_e32 v22, v148, v149, vcc
	v_mul_f32_e32 v0, v22, v21
	v_exp_f32_e32 v21, v0
	v_pk_mul_f32 v[0:1], v[18:19], v[8:9]
	v_cmp_lt_i32_e32 vcc, s20, v137
	v_cvt_pk_bf16_f32 v132, v0, v1
	ds_read_b128 v[0:3], v27 offset:26176
	s_waitcnt lgkmcnt(1)
; __device__ __forceinline__ f32x16 mfma32(bf16x8 a, bf16x8 b, f32x16 c) { return __builtin_amdgcn_mfma_f32_32x32x16_bf16(a, b, c, 0, 0, 0); }
; __device__ void ret_out_item(const bf16_t* __restrict__ Qb, const bf16_t* __restrict__ Kb, bf16_t* Vb, const bf16_t* __restrict__ STf, const bf16_t* __restrict__ STb,
;                              int cidx, int head, float lgf2, float lgb2, LAS unsigned char* lds) {
;     ...
;   f32x16 acc[4];
; #pragma unroll
;   for (int i = 0; i < 4; ++i) acc[i] = (f32x16){};
;   const unsigned cofs = (unsigned)(eh * 128 + 16 * G1 + 4 * p4) * 2u;
; #pragma unroll
;   for (int jt = 0; jt < 4; ++jt)
; #pragma unroll
;     for (int s = 0; s < 2; ++s) {
;       const unsigned r = (unsigned)(jt * 32 + 16 * s + 4 * h + q4);
; #pragma unroll
;       for (int et = 0; et < 4; ++et) acc[et] = mfma32(tr_frag(lds, r * VS + et * 64 + cofs, (r + 8) * VS + et * 64 + cofs), pf[jt][s], acc[et]);
;     }
	v_mfma_f32_32x32x16_bf16 v[64:79], v[4:7], v[104:107], v[64:79]
	v_add_u32_e32 v4, 0xffffffa8, v137
	v_sub_u32_e32 v5, 0x58, v137
	v_cndmask_b32_e32 v4, v5, v4, vcc
	v_mul_f32_e64 v8, v20, v10
	v_mul_f32_e64 v9, v21, v11
	v_cvt_f32_u32_e32 v10, v4
	ds_read_b128 v[4:7], v27 offset:26208
	v_cndmask_b32_e32 v11, v148, v149, vcc
	s_waitcnt lgkmcnt(1)
	v_mfma_f32_32x32x16_bf16 v[64:79], v[0:3], v[100:103], v[64:79]
	v_mul_f32_e32 v0, v11, v10
	s_movk_i32 s20, 0x58
	v_exp_f32_e32 v10, v0
	v_add_u32_e32 v0, 0xffffffa7, v137
	v_sub_u32_e32 v1, 0x59, v137
	v_cmp_lt_i32_e32 vcc, s20, v137
	s_movk_i32 s20, 0x59
	s_waitcnt lgkmcnt(0)
	v_mfma_f32_32x32x16_bf16 v[64:79], v[4:7], v[96:99], v[64:79]
	v_cndmask_b32_e32 v11, v1, v0, vcc
	ds_read_b128 v[0:3], v27 offset:26240
	v_cndmask_b32_e32 v16, v148, v149, vcc
	v_add_u32_e32 v4, 0xffffffa6, v137
	v_sub_u32_e32 v5, 0x5a, v137
	v_cmp_lt_i32_e32 vcc, s20, v137
	v_cvt_f32_u32_e32 v11, v11
	s_movk_i32 s20, 0x5a
	v_cndmask_b32_e32 v17, v5, v4, vcc
	ds_read_b128 v[4:7], v27 offset:26272
	s_waitcnt lgkmcnt(1)
	v_mfma_f32_32x32x16_bf16 v[64:79], v[0:3], v[92:95], v[64:79]
	v_cvt_f32_u32_e32 v0, v17
	v_mul_f32_e32 v1, v16, v11
	v_exp_f32_e32 v11, v1
	v_cndmask_b32_e32 v1, v148, v149, vcc
	v_mul_f32_e32 v0, v1, v0
	v_exp_f32_e32 v16, v0
	ds_read_b128 v[0:3], v27 offset:26304
	s_waitcnt lgkmcnt(1)
	v_mfma_f32_32x32x16_bf16 v[64:79], v[4:7], v[88:91], v[64:79]
	v_add_u32_e32 v4, 0xffffffa5, v137
	v_sub_u32_e32 v5, 0x5b, v137
	v_cmp_lt_i32_e32 vcc, s20, v137
	s_movk_i32 s20, 0x5f
	v_cvt_pk_bf16_f32 v133, v8, v9
	v_cndmask_b32_e32 v4, v5, v4, vcc
	v_cvt_f32_u32_e32 v17, v4
	v_cndmask_b32_e32 v18, v148, v149, vcc
	ds_read_b128 v[4:7], v27 offset:26336
	s_waitcnt lgkmcnt(1)
	v_mfma_f32_32x32x16_bf16 v[64:79], v[0:3], v[84:87], v[64:79]
	v_mul_f32_e32 v0, v18, v17
	v_exp_f32_e32 v17, v0
	v_pk_mul_f32 v[0:1], v[10:11], v[12:13]
	v_cmp_lt_i32_e32 vcc, s20, v137
	v_cvt_pk_bf16_f32 v134, v0, v1
	v_pk_mul_f32 v[0:1], v[16:17], v[14:15]
	s_movk_i32 s20, 0x61
	v_cvt_pk_bf16_f32 v135, v0, v1
	v_add_u32_e32 v0, 0xffffffa0, v137
	v_sub_u32_e32 v1, 0x60, v137
	v_cndmask_b32_e32 v0, v1, v0, vcc
	v_ashrrev_i32_e32 v1, 1, v24
	v_and_b32_e32 v136, 0xffffff80, v1
	v_lshlrev_b32_e32 v1, 2, v24
	s_waitcnt lgkmcnt(0)
	v_mfma_f32_32x32x16_bf16 v[64:79], v[4:7], v[80:83], v[64:79]
	v_cvt_f32_u32_e32 v4, v0
	v_and_b32_e32 v0, 16, v24
	v_and_b32_e32 v1, 12, v1
	v_or3_b32 v0, v1, v0, v136
	v_and_or_b32 v1, v25, 3, v26
	v_lshlrev_b32_e32 v0, 1, v0
	v_mul_u32_u24_e32 v1, 0x240, v1
	v_add3_u32 v151, 0, v0, v1
	v_add3_u32 v180, 0, v1, v0
	ds_read_b64_tr_b16 v[0:1], v151
	ds_read_b64_tr_b16 v[2:3], v180 offset:4608
	v_cndmask_b32_e32 v5, v148, v149, vcc
	s_waitcnt lgkmcnt(0)
	v_mfma_f32_32x32x16_bf16 v[48:63], v[0:3], v[112:115], 0
	v_add_u32_e32 v0, 0xffffff9f, v137
	v_sub_u32_e32 v1, 0x61, v137
	v_cmp_lt_i32_e32 vcc, s34, v137
	v_mul_f32_e32 v16, v5, v4
	ds_read_b64_tr_b16 v[4:5], v151 offset:64
	ds_read_b64_tr_b16 v[8:9], v151 offset:128
	ds_read_b64_tr_b16 v[12:13], v151 offset:192
	ds_read_b64_tr_b16 v[6:7], v180 offset:4672
	ds_read_b64_tr_b16 v[10:11], v180 offset:4736
	ds_read_b64_tr_b16 v[14:15], v180 offset:4800
	v_cndmask_b32_e32 v0, v1, v0, vcc
	v_cvt_f32_u32_e32 v0, v0
	v_cndmask_b32_e32 v1, v148, v149, vcc
	v_cmp_lt_i32_e32 vcc, s20, v137
	s_movk_i32 s20, 0x62
	v_mul_f32_e32 v0, v1, v0
	v_exp_f32_e32 v179, v0
	v_add_u32_e32 v0, 0xffffff9e, v137
	v_sub_u32_e32 v1, 0x62, v137
	v_cndmask_b32_e32 v0, v1, v0, vcc
	v_cndmask_b32_e32 v181, v148, v149, vcc
	v_cvt_f32_u32_e32 v182, v0
	v_add_u32_e32 v0, 0xffffff9d, v137
	v_sub_u32_e32 v1, 0x63, v137
	v_cmp_lt_i32_e32 vcc, s20, v137
	ds_read_b64_tr_b16 v[152:153], v151 offset:9216
	ds_read_b64_tr_b16 v[154:155], v180 offset:13824
	v_cndmask_b32_e32 v156, v1, v0, vcc
	v_cvt_f32_u32_e32 v183, v156
	s_waitcnt lgkmcnt(4)
	v_mfma_f32_32x32x16_bf16 v[32:47], v[4:7], v[112:115], 0
	v_exp_f32_e32 v178, v16
	s_movk_i32 s20, 0x67
	v_readlane_b32 s34, v250, 51
	v_readlane_b32 s35, v250, 52
	v_pk_mul_f32 v[64:65], v[178:179], v[64:65]
	s_nop 0
	v_cvt_pk_bf16_f32 v64, v64, v65
	s_waitcnt lgkmcnt(0)
	v_mfma_f32_32x32x16_bf16 v[48:63], v[152:155], v[116:119], v[48:63]
	v_cndmask_b32_e32 v153, v148, v149, vcc
	v_mul_f32_e32 v152, v181, v182
	v_mul_f32_e32 v153, v153, v183
	v_exp_f32_e32 v152, v152
	v_exp_f32_e32 v153, v153
	v_cmp_lt_i32_e32 vcc, s20, v137
	s_movk_i32 s20, 0x68
	v_mfma_f32_32x32x16_bf16 v[16:31], v[8:11], v[112:115], 0
	v_mul_f32_e64 v66, v152, v66
	v_mul_f32_e64 v67, v153, v67
	v_cvt_pk_bf16_f32 v65, v66, v67
	v_add_u32_e32 v66, 0xffffff98, v137
	v_sub_u32_e32 v67, 0x68, v137
	v_cndmask_b32_e32 v66, v67, v66, vcc
	v_cndmask_b32_e32 v67, v148, v149, vcc
	v_mfma_f32_32x32x16_bf16 v[0:15], v[12:15], v[112:115], 0
	ds_read_b64_tr_b16 v[112:113], v151 offset:9280
	ds_read_b64_tr_b16 v[156:157], v151 offset:9344
	ds_read_b64_tr_b16 v[174:175], v151 offset:9408
	ds_read_b64_tr_b16 v[114:115], v180 offset:13888
	ds_read_b64_tr_b16 v[158:159], v180 offset:13952
	ds_read_b64_tr_b16 v[176:177], v180 offset:14016
	v_cmp_lt_i32_e32 vcc, s20, v137
	v_cvt_f32_u32_e32 v66, v66
	s_movk_i32 s20, 0x69
	v_mul_f32_e32 v66, v67, v66
	s_waitcnt lgkmcnt(2)
	v_mfma_f32_32x32x16_bf16 v[32:47], v[112:115], v[116:119], v[32:47]
	v_add_u32_e32 v112, 0xffffff97, v137
	v_sub_u32_e32 v113, 0x69, v137
	v_cndmask_b32_e32 v152, v113, v112, vcc
	ds_read_b64_tr_b16 v[112:113], v151 offset:18432
	ds_read_b64_tr_b16 v[114:115], v180 offset:23040
	v_cndmask_b32_e32 v67, v148, v149, vcc
	v_cmp_lt_i32_e32 vcc, s20, v137
	s_movk_i32 s20, 0x6a
	s_waitcnt lgkmcnt(0)
; __device__ __forceinline__ f32x16 mfma32(bf16x8 a, bf16x8 b, f32x16 c) { return __builtin_amdgcn_mfma_f32_32x32x16_bf16(a, b, c, 0, 0, 0); }
; __device__ void ret_out_item(const bf16_t* __restrict__ Qb, const bf16_t* __restrict__ Kb, bf16_t* Vb, const bf16_t* __restrict__ STf, const bf16_t* __restrict__ STb,
;                              int cidx, int head, float lgf2, float lgb2, LAS unsigned char* lds) {
;     ...
; #pragma unroll
;   for (int jt = 0; jt < 4; ++jt)
; #pragma unroll
;     for (int s = 0; s < 2; ++s) {
;       const unsigned r = (unsigned)(jt * 32 + 16 * s + 4 * h + q4);
; #pragma unroll
;       for (int et = 0; et < 4; ++et) acc[et] = mfma32(tr_frag(lds, r * VS + et * 64 + cofs, (r + 8) * VS + et * 64 + cofs), pf[jt][s], acc[et]);
;     }
	v_mfma_f32_32x32x16_bf16 v[48:63], v[112:115], v[120:123], v[48:63]
	v_add_u32_e32 v112, 0xffffff96, v137
	v_sub_u32_e32 v113, 0x6a, v137
	v_cndmask_b32_e32 v112, v113, v112, vcc
	v_cndmask_b32_e32 v113, v148, v149, vcc
	v_cvt_f32_u32_e32 v112, v112
	v_add_u32_e32 v114, 0xffffff95, v137
	v_sub_u32_e32 v115, 0x6b, v137
	v_mfma_f32_32x32x16_bf16 v[0:15], v[174:177], v[116:119], v[0:15]
	v_cvt_f32_u32_e32 v174, v152
	v_cmp_lt_i32_e32 vcc, s20, v137
	v_exp_f32_e32 v66, v66
	v_mul_f32_e32 v112, v113, v112
	v_cndmask_b32_e32 v114, v115, v114, vcc
	v_cvt_f32_u32_e32 v114, v114
	v_mul_f32_e32 v67, v67, v174
	v_mfma_f32_32x32x16_bf16 v[16:31], v[156:159], v[116:119], v[16:31]
	ds_read_b64_tr_b16 v[116:117], v151 offset:18496
	ds_read_b64_tr_b16 v[152:153], v151 offset:18560
	ds_read_b64_tr_b16 v[156:157], v151 offset:18624
	ds_read_b64_tr_b16 v[118:119], v180 offset:23104
	ds_read_b64_tr_b16 v[154:155], v180 offset:23168
	ds_read_b64_tr_b16 v[158:159], v180 offset:23232
	v_exp_f32_e32 v67, v67
	v_exp_f32_e32 v174, v112
	v_cndmask_b32_e32 v112, v148, v149, vcc
	s_movk_i32 s20, 0x6f
	v_pk_mul_f32 v[66:67], v[66:67], v[68:69]
	v_sub_u32_e32 v68, 0x70, v137
	s_waitcnt lgkmcnt(2)
	v_mfma_f32_32x32x16_bf16 v[32:47], v[116:119], v[120:123], v[32:47]
	v_mul_f32_e32 v116, v112, v114
	v_exp_f32_e32 v175, v116
	ds_read_b64_tr_b16 v[112:113], v151 offset:27648
	ds_read_b64_tr_b16 v[114:115], v180 offset:32256
	v_cvt_pk_bf16_f32 v66, v66, v67
	v_add_u32_e32 v67, 0xffffff90, v137
	v_cmp_lt_i32_e32 vcc, s20, v137
	s_movk_i32 s20, 0x70
	s_waitcnt lgkmcnt(2)
	v_mfma_f32_32x32x16_bf16 v[0:15], v[156:159], v[120:123], v[0:15]
	v_cndmask_b32_e32 v67, v68, v67, vcc
	v_mul_f32_e64 v156, v174, v70
	v_mul_f32_e64 v157, v175, v71
	v_cndmask_b32_e32 v68, v148, v149, vcc
	v_cvt_f32_u32_e32 v67, v67
	v_add_u32_e32 v69, 0xffffff8f, v137
	v_sub_u32_e32 v70, 0x71, v137
	v_cmp_lt_i32_e32 vcc, s20, v137
	s_waitcnt lgkmcnt(0)
	v_mfma_f32_32x32x16_bf16 v[48:63], v[112:115], v[124:127], v[48:63]
	v_mul_f32_e32 v67, v68, v67
	v_cndmask_b32_e32 v69, v70, v69, vcc
	v_cvt_f32_u32_e32 v69, v69
	v_exp_f32_e32 v158, v67
	v_cndmask_b32_e32 v67, v148, v149, vcc
	s_movk_i32 s20, 0x71
	v_mul_f32_e32 v67, v67, v69
	v_mfma_f32_32x32x16_bf16 v[16:31], v[152:155], v[120:123], v[16:31]
	ds_read_b64_tr_b16 v[116:117], v151 offset:27712
	ds_read_b64_tr_b16 v[120:121], v151 offset:27776
	ds_read_b64_tr_b16 v[152:153], v151 offset:27840
	ds_read_b64_tr_b16 v[118:119], v180 offset:32320
	ds_read_b64_tr_b16 v[122:123], v180 offset:32384
	ds_read_b64_tr_b16 v[154:155], v180 offset:32448
	ds_read_b64_tr_b16 v[68:69], v151 offset:36864
	ds_read_b64_tr_b16 v[70:71], v180 offset:41472
	v_exp_f32_e32 v159, v67
	v_add_u32_e32 v67, 0xffffff8e, v137
	v_cmp_lt_i32_e32 vcc, s20, v137
	s_movk_i32 s20, 0x72
	s_waitcnt lgkmcnt(0)
	v_mfma_f32_32x32x16_bf16 v[48:63], v[68:71], v[128:131], v[48:63]
	v_sub_u32_e32 v68, 0x72, v137
	v_cndmask_b32_e32 v67, v68, v67, vcc
	v_cndmask_b32_e32 v68, v148, v149, vcc
	v_cvt_f32_u32_e32 v67, v67
	v_add_u32_e32 v69, 0xffffff8d, v137
	v_sub_u32_e32 v70, 0x73, v137
	v_cmp_lt_i32_e32 vcc, s20, v137
	v_mul_f32_e32 v67, v68, v67
	v_mfma_f32_32x32x16_bf16 v[32:47], v[116:119], v[124:127], v[32:47]
	v_cndmask_b32_e32 v69, v70, v69, vcc
	v_cvt_f32_u32_e32 v69, v69
	v_exp_f32_e32 v70, v67
	v_cndmask_b32_e32 v67, v148, v149, vcc
	s_movk_i32 s20, 0x77
	v_mul_f32_e32 v67, v67, v69
	v_exp_f32_e32 v71, v67
	v_mfma_f32_32x32x16_bf16 v[16:31], v[120:123], v[124:127], v[16:31]
	ds_read_b64_tr_b16 v[112:113], v151 offset:36928
	ds_read_b64_tr_b16 v[116:117], v151 offset:36992
	ds_read_b64_tr_b16 v[120:121], v151 offset:37056
	ds_read_b64_tr_b16 v[114:115], v180 offset:41536
	ds_read_b64_tr_b16 v[118:119], v180 offset:41600
	ds_read_b64_tr_b16 v[122:123], v180 offset:41664
	v_pk_mul_f32 v[68:69], v[158:159], v[72:73]
	v_pk_mul_f32 v[74:75], v[70:71], v[74:75]
	ds_read_b64_tr_b16 v[70:71], v151 offset:46080
	ds_read_b64_tr_b16 v[72:73], v180 offset:50688
	v_cvt_pk_bf16_f32 v68, v68, v69
	v_add_u32_e32 v69, 0xffffff88, v137
	v_cmp_lt_i32_e32 vcc, s20, v137
	s_waitcnt lgkmcnt(0)
	v_mfma_f32_32x32x16_bf16 v[48:63], v[70:73], v[132:135], v[48:63]
	v_sub_u32_e32 v70, 0x78, v137
	v_cndmask_b32_e32 v69, v70, v69, vcc
	s_movk_i32 s20, 0x78
	v_cndmask_b32_e32 v70, v148, v149, vcc
	v_cvt_f32_u32_e32 v69, v69
	v_add_u32_e32 v71, 0xffffff87, v137
	v_sub_u32_e32 v72, 0x79, v137
	v_mfma_f32_32x32x16_bf16 v[0:15], v[152:155], v[124:127], v[0:15]
	v_cmp_lt_i32_e32 vcc, s20, v137
	v_mul_f32_e32 v69, v70, v69
	v_exp_f32_e32 v124, v69
	v_cndmask_b32_e32 v71, v72, v71, vcc
	v_cvt_f32_u32_e32 v71, v71
	v_cndmask_b32_e32 v69, v148, v149, vcc
	s_movk_i32 s20, 0x79
	v_sub_u32_e32 v70, 0x7a, v137
	v_mul_f32_e32 v69, v69, v71
	v_exp_f32_e32 v125, v69
	v_add_u32_e32 v69, 0xffffff86, v137
	v_cmp_lt_i32_e32 vcc, s20, v137
	v_mfma_f32_32x32x16_bf16 v[32:47], v[112:115], v[128:131], v[32:47]
	v_cvt_pk_bf16_f32 v67, v156, v157
	v_cndmask_b32_e32 v69, v70, v69, vcc
	s_movk_i32 s20, 0x7a
	v_cndmask_b32_e32 v126, v148, v149, vcc
	v_cvt_f32_u32_e32 v69, v69
	v_cmp_lt_i32_e32 vcc, s20, v137
	s_movk_i32 s20, 0x2000
	v_mfma_f32_32x32x16_bf16 v[16:31], v[116:119], v[128:131], v[16:31]
	v_mul_f32_e32 v69, v126, v69
	v_mfma_f32_32x32x16_bf16 v[0:15], v[120:123], v[128:131], v[0:15]
	ds_read_b64_tr_b16 v[112:113], v151 offset:46144
	ds_read_b64_tr_b16 v[116:117], v151 offset:46208
	ds_read_b64_tr_b16 v[120:121], v151 offset:46272
	ds_read_b64_tr_b16 v[114:115], v180 offset:50752
	ds_read_b64_tr_b16 v[118:119], v180 offset:50816
	ds_read_b64_tr_b16 v[122:123], v180 offset:50880
	ds_read_b64_tr_b16 v[70:71], v151 offset:55296
	ds_read_b64_tr_b16 v[72:73], v180 offset:59904
	s_waitcnt lgkmcnt(0)
; __device__ __forceinline__ f32x16 mfma32(bf16x8 a, bf16x8 b, f32x16 c) { return __builtin_amdgcn_mfma_f32_32x32x16_bf16(a, b, c, 0, 0, 0); }
; __device__ void ret_out_item(const bf16_t* __restrict__ Qb, const bf16_t* __restrict__ Kb, bf16_t* Vb, const bf16_t* __restrict__ STf, const bf16_t* __restrict__ STb,
;                              int cidx, int head, float lgf2, float lgb2, LAS unsigned char* lds) {
;     ...
;   const unsigned cofs = (unsigned)(eh * 128 + 16 * G1 + 4 * p4) * 2u;
; #pragma unroll
;   for (int jt = 0; jt < 4; ++jt)
; #pragma unroll
;     for (int s = 0; s < 2; ++s) {
;       const unsigned r = (unsigned)(jt * 32 + 16 * s + 4 * h + q4);
; #pragma unroll
;       for (int et = 0; et < 4; ++et) acc[et] = mfma32(tr_frag(lds, r * VS + et * 64 + cofs, (r + 8) * VS + et * 64 + cofs), pf[jt][s], acc[et]);
;     }
; #pragma unroll
;   for (int dir = 0; dir < 2; ++dir) {
;     const float xi = dir ? __builtin_amdgcn_exp2f(lgb2 * (float)(128 - iloc)) : __builtin_amdgcn_exp2f(lgf2 * (float)(iloc + 1));
;     const bf16_t* sp = (dir ? STb : STf) + ((size_t)(cidx * 4 + head) * 256 + eh * 128 + il) * 128 + 8 * h;
; #pragma unroll
;     for (int kp = 0; kp < 4; ++kp) {
;       bf16x8 sf[2][4];
; #pragma unroll
;       for (int k2 = 0; k2 < 2; ++k2)
; #pragma unroll
;         for (int et = 0; et < 4; ++et) sf[k2][et] = *(const bf16x8*)(sp + (size_t)et * 32 * 128 + 16 * (2 * kp + k2));
; #pragma unroll
;       for (int k2 = 0; k2 < 2; ++k2) {
;         const bf16x8 sq = scale_frag(qf[2 * kp + k2], xi);
; #pragma unroll
;         for (int et = 0; et < 4; ++et) acc[et] = mfma32(sf[k2][et], sq, acc[et]);
;       }
;     }
;   }
	v_mfma_f32_32x32x16_bf16 v[48:63], v[70:73], v[64:67], v[48:63]
	v_add_u32_e32 v70, 0xffffff85, v137
	v_sub_u32_e32 v71, 0x7b, v137
	v_cndmask_b32_e32 v70, v71, v70, vcc
	v_cvt_f32_u32_e32 v70, v70
	v_exp_f32_e32 v72, v69
	v_cndmask_b32_e32 v69, v148, v149, vcc
	v_ashrrev_i32_e32 v137, 31, v136
	v_mul_f32_e32 v69, v69, v70
	v_mfma_f32_32x32x16_bf16 v[32:47], v[112:115], v[132:135], v[32:47]
	v_exp_f32_e32 v73, v69
	v_cvt_pk_bf16_f32 v69, v74, v75
	v_pk_mul_f32 v[70:71], v[124:125], v[76:77]
	v_pk_mul_f32 v[78:79], v[72:73], v[78:79]
	v_or_b32_e32 v72, v136, v150
	v_mov_b32_e32 v73, v137
	v_mfma_f32_32x32x16_bf16 v[16:31], v[116:119], v[132:135], v[16:31]
	v_lshl_add_u64 v[72:73], s[22:23], 0, v[72:73]
	v_lshlrev_b64 v[72:73], 8, v[72:73]
	v_lshl_add_u64 v[74:75], s[34:35], 0, v[72:73]
	v_cvt_pk_bf16_f32 v70, v70, v71
	v_cvt_pk_bf16_f32 v71, v78, v79
	v_readlane_b32 s34, v250, 53
	v_readlane_b32 s35, v250, 54
	v_mfma_f32_32x32x16_bf16 v[0:15], v[120:123], v[132:135], v[0:15]
	ds_read_b64_tr_b16 v[112:113], v151 offset:55360
	ds_read_b64_tr_b16 v[116:117], v151 offset:55424
	ds_read_b64_tr_b16 v[120:121], v151 offset:55488
	ds_read_b64_tr_b16 v[114:115], v180 offset:59968
	ds_read_b64_tr_b16 v[118:119], v180 offset:60032
	ds_read_b64_tr_b16 v[122:123], v180 offset:60096
	v_lshl_add_u64 v[72:73], s[34:35], 0, v[72:73]
	s_waitcnt lgkmcnt(2)
	v_mfma_f32_32x32x16_bf16 v[32:47], v[112:115], v[64:67], v[32:47]
	v_lshl_add_u64 v[112:113], v[74:75], 0, v[160:161]
	v_add_u32_e32 v114, 0xfc00, v180
	s_waitcnt lgkmcnt(1)
	v_mfma_f32_32x32x16_bf16 v[16:31], v[116:119], v[64:67], v[16:31]
	global_load_dwordx4 v[116:119], v[112:113], off
	ds_read_b64_tr_b16 v[74:75], v151 offset:64512
	ds_read_b64_tr_b16 v[76:77], v114 offset:4608
	s_waitcnt lgkmcnt(0)
	v_mfma_f32_32x32x16_bf16 v[48:63], v[74:77], v[68:71], v[48:63]
	v_add_co_u32_e32 v74, vcc, s20, v112
	s_nop 1
	v_addc_co_u32_e32 v75, vcc, 0, v113, vcc
	v_add_co_u32_e32 v76, vcc, s36, v112
	v_mfma_f32_32x32x16_bf16 v[0:15], v[120:123], v[64:67], v[0:15]
	ds_read_b64_tr_b16 v[64:65], v151 offset:64576
	ds_read_b64_tr_b16 v[120:121], v151 offset:64640
	ds_read_b64_tr_b16 v[124:125], v151 offset:64704
	ds_read_b64_tr_b16 v[66:67], v114 offset:4672
	ds_read_b64_tr_b16 v[122:123], v114 offset:4736
	ds_read_b64_tr_b16 v[126:127], v114 offset:4800
	global_load_dwordx4 v[128:131], v[74:75], off
	v_addc_co_u32_e32 v77, vcc, 0, v113, vcc
	global_load_dwordx4 v[132:135], v[76:77], off
	v_add_co_u32_e32 v114, vcc, s37, v112
	s_waitcnt lgkmcnt(1)
	v_mfma_f32_32x32x16_bf16 v[16:31], v[120:123], v[68:71], v[16:31]
	v_addc_co_u32_e32 v115, vcc, 0, v113, vcc
	global_load_dwordx4 v[120:123], v[114:115], off
	global_load_dwordx4 v[150:153], v[112:113], off offset:32
	s_waitcnt lgkmcnt(0)
	v_mfma_f32_32x32x16_bf16 v[0:15], v[124:127], v[68:71], v[0:15]
	global_load_dwordx4 v[124:127], v[74:75], off offset:32
	v_mfma_f32_32x32x16_bf16 v[32:47], v[64:67], v[68:71], v[32:47]
	v_add_u32_e32 v64, 1, v147
	v_cvt_f32_ubyte0_e32 v64, v64
	v_mul_f32_e32 v64, v149, v64
	v_exp_f32_e32 v64, v64
	v_lshlrev_b32_e32 v66, 16, v108
	v_and_b32_e32 v67, 0xffff0000, v108
	v_pk_mul_f32 v[68:69], v[64:65], v[66:67] op_sel_hi:[0,1]
	v_cvt_pk_bf16_f32 v108, v68, v69
	v_lshlrev_b32_e32 v68, 16, v109
	v_and_b32_e32 v69, 0xffff0000, v109
	v_pk_mul_f32 v[70:71], v[64:65], v[68:69] op_sel_hi:[0,1]
	v_cvt_pk_bf16_f32 v109, v70, v71
	v_lshlrev_b32_e32 v70, 16, v110
	v_and_b32_e32 v71, 0xffff0000, v110
	v_pk_mul_f32 v[78:79], v[64:65], v[70:71] op_sel_hi:[0,1]
	v_cvt_pk_bf16_f32 v110, v78, v79
	v_lshlrev_b32_e32 v78, 16, v111
	v_and_b32_e32 v79, 0xffff0000, v111
	v_pk_mul_f32 v[154:155], v[64:65], v[78:79] op_sel_hi:[0,1]
	v_cvt_pk_bf16_f32 v111, v154, v155
	s_waitcnt vmcnt(5)
	s_nop 0
	v_mfma_f32_32x32x16_bf16 v[48:63], v[116:119], v[108:111], v[48:63]
	global_load_dwordx4 v[116:119], v[76:77], off offset:32
	s_waitcnt vmcnt(5)
	v_mfma_f32_32x32x16_bf16 v[32:47], v[128:131], v[108:111], v[32:47]
	global_load_dwordx4 v[128:131], v[114:115], off offset:32
	s_waitcnt vmcnt(5)
	v_mfma_f32_32x32x16_bf16 v[16:31], v[132:135], v[108:111], v[16:31]
	global_load_dwordx4 v[132:135], v[112:113], off offset:64
	s_waitcnt vmcnt(5)
	v_mfma_f32_32x32x16_bf16 v[0:15], v[120:123], v[108:111], v[0:15]
	v_lshlrev_b32_e32 v108, 16, v104
	v_and_b32_e32 v109, 0xffff0000, v104
	v_mul_f32_e64 v110, v64, v108
	v_mul_f32_e64 v111, v64, v109
	v_lshlrev_b32_e32 v104, 16, v105
	v_and_b32_e32 v105, 0xffff0000, v105
	v_cvt_pk_bf16_f32 v120, v110, v111
	v_pk_mul_f32 v[110:111], v[64:65], v[104:105] op_sel_hi:[0,1]
	v_cvt_pk_bf16_f32 v121, v110, v111
	v_lshlrev_b32_e32 v110, 16, v106
	v_and_b32_e32 v111, 0xffff0000, v106
	v_lshlrev_b32_e32 v106, 16, v107
	v_and_b32_e32 v107, 0xffff0000, v107
	v_pk_mul_f32 v[122:123], v[64:65], v[110:111] op_sel_hi:[0,1]
	v_pk_mul_f32 v[154:155], v[64:65], v[106:107] op_sel_hi:[0,1]
	v_cvt_pk_bf16_f32 v122, v122, v123
	v_cvt_pk_bf16_f32 v123, v154, v155
	s_waitcnt vmcnt(4)
	s_nop 0
	v_mfma_f32_32x32x16_bf16 v[48:63], v[150:153], v[120:123], v[48:63]
	global_load_dwordx4 v[150:153], v[74:75], off offset:64
	s_waitcnt vmcnt(4)
	v_mfma_f32_32x32x16_bf16 v[32:47], v[124:127], v[120:123], v[32:47]
	global_load_dwordx4 v[124:127], v[76:77], off offset:64
	global_load_dwordx4 v[154:157], v[114:115], off offset:64
	global_load_dwordx4 v[174:177], v[112:113], off offset:96
	s_waitcnt vmcnt(6)
	v_mfma_f32_32x32x16_bf16 v[16:31], v[116:119], v[120:123], v[16:31]
	v_lshlrev_b32_e32 v116, 16, v100
	v_and_b32_e32 v117, 0xffff0000, v100
	v_mul_f32_e64 v118, v64, v116
	v_mul_f32_e64 v119, v64, v117
	v_lshlrev_b32_e32 v100, 16, v101
	v_and_b32_e32 v101, 0xffff0000, v101
	s_waitcnt vmcnt(5)
; __device__ __forceinline__ f32x16 mfma32(bf16x8 a, bf16x8 b, f32x16 c) { return __builtin_amdgcn_mfma_f32_32x32x16_bf16(a, b, c, 0, 0, 0); }
; __device__ void ret_out_item(const bf16_t* __restrict__ Qb, const bf16_t* __restrict__ Kb, bf16_t* Vb, const bf16_t* __restrict__ STf, const bf16_t* __restrict__ STb,
;                              int cidx, int head, float lgf2, float lgb2, LAS unsigned char* lds) {
;     ...
;   for (int dir = 0; dir < 2; ++dir) {
;     const float xi = dir ? __builtin_amdgcn_exp2f(lgb2 * (float)(128 - iloc)) : __builtin_amdgcn_exp2f(lgf2 * (float)(iloc + 1));
;     const bf16_t* sp = (dir ? STb : STf) + ((size_t)(cidx * 4 + head) * 256 + eh * 128 + il) * 128 + 8 * h;
; #pragma unroll
;     for (int kp = 0; kp < 4; ++kp) {
;       bf16x8 sf[2][4];
; #pragma unroll
;       for (int k2 = 0; k2 < 2; ++k2)
; #pragma unroll
;         for (int et = 0; et < 4; ++et) sf[k2][et] = *(const bf16x8*)(sp + (size_t)et * 32 * 128 + 16 * (2 * kp + k2));
; #pragma unroll
;       for (int k2 = 0; k2 < 2; ++k2) {
;         const bf16x8 sq = scale_frag(qf[2 * kp + k2], xi);
; #pragma unroll
;         for (int et = 0; et < 4; ++et) acc[et] = mfma32(sf[k2][et], sq, acc[et]);
;       }
;     }
	v_mfma_f32_32x32x16_bf16 v[0:15], v[128:131], v[120:123], v[0:15]
	v_cvt_pk_bf16_f32 v120, v118, v119
	v_mul_f32_e64 v118, v64, v100
	v_mul_f32_e64 v119, v64, v101
	v_cvt_pk_bf16_f32 v121, v118, v119
	v_lshlrev_b32_e32 v118, 16, v102
	v_and_b32_e32 v119, 0xffff0000, v102
	v_lshlrev_b32_e32 v102, 16, v103
	v_and_b32_e32 v103, 0xffff0000, v103
	v_pk_mul_f32 v[122:123], v[64:65], v[118:119] op_sel_hi:[0,1]
	v_pk_mul_f32 v[128:129], v[64:65], v[102:103] op_sel_hi:[0,1]
	v_cvt_pk_bf16_f32 v122, v122, v123
	v_cvt_pk_bf16_f32 v123, v128, v129
	global_load_dwordx4 v[128:131], v[74:75], off offset:96
	s_waitcnt vmcnt(5)
	v_mfma_f32_32x32x16_bf16 v[48:63], v[132:135], v[120:123], v[48:63]
	global_load_dwordx4 v[132:135], v[76:77], off offset:96
	s_waitcnt vmcnt(5)
	v_mfma_f32_32x32x16_bf16 v[32:47], v[150:153], v[120:123], v[32:47]
	s_waitcnt vmcnt(4)
	v_mfma_f32_32x32x16_bf16 v[16:31], v[124:127], v[120:123], v[16:31]
	global_load_dwordx4 v[124:127], v[114:115], off offset:96
	global_load_dwordx4 v[150:153], v[112:113], off offset:128
	s_waitcnt vmcnt(5)
	v_mfma_f32_32x32x16_bf16 v[0:15], v[154:157], v[120:123], v[0:15]
	v_lshlrev_b32_e32 v120, 16, v96
	v_and_b32_e32 v121, 0xffff0000, v96
	v_mul_f32_e64 v122, v64, v120
	v_mul_f32_e64 v123, v64, v121
	v_lshlrev_b32_e32 v96, 16, v97
	v_and_b32_e32 v97, 0xffff0000, v97
	v_cvt_pk_bf16_f32 v154, v122, v123
	v_pk_mul_f32 v[122:123], v[64:65], v[96:97] op_sel_hi:[0,1]
	v_cvt_pk_bf16_f32 v155, v122, v123
	v_lshlrev_b32_e32 v122, 16, v98
	v_and_b32_e32 v123, 0xffff0000, v98
	v_lshlrev_b32_e32 v98, 16, v99
	v_and_b32_e32 v99, 0xffff0000, v99
	v_pk_mul_f32 v[156:157], v[64:65], v[122:123] op_sel_hi:[0,1]
	v_pk_mul_f32 v[158:159], v[64:65], v[98:99] op_sel_hi:[0,1]
	v_cvt_pk_bf16_f32 v156, v156, v157
	v_cvt_pk_bf16_f32 v157, v158, v159
	s_waitcnt vmcnt(4)
	s_nop 0
	v_mfma_f32_32x32x16_bf16 v[48:63], v[174:177], v[154:157], v[48:63]
	global_load_dwordx4 v[174:177], v[74:75], off offset:128
	s_waitcnt vmcnt(4)
	v_mfma_f32_32x32x16_bf16 v[32:47], v[128:131], v[154:157], v[32:47]
	global_load_dwordx4 v[128:131], v[76:77], off offset:128
	s_waitcnt vmcnt(3)
	v_mfma_f32_32x32x16_bf16 v[0:15], v[124:127], v[154:157], v[0:15]
	v_lshlrev_b32_e32 v124, 16, v92
	v_and_b32_e32 v125, 0xffff0000, v92
	v_mul_f32_e64 v126, v64, v124
	v_mul_f32_e64 v127, v64, v125
	v_lshlrev_b32_e32 v92, 16, v93
	v_and_b32_e32 v93, 0xffff0000, v93
	v_mfma_f32_32x32x16_bf16 v[16:31], v[132:135], v[154:157], v[16:31]
	global_load_dwordx4 v[132:135], v[114:115], off offset:128
	global_load_dwordx4 v[178:181], v[112:113], off offset:160
	global_load_dwordx4 v[182:185], v[74:75], off offset:160
	v_cvt_pk_bf16_f32 v154, v126, v127
	v_mul_f32_e64 v126, v64, v92
	v_mul_f32_e64 v127, v64, v93
	v_cvt_pk_bf16_f32 v155, v126, v127
	v_lshlrev_b32_e32 v126, 16, v94
	v_and_b32_e32 v127, 0xffff0000, v94
	v_lshlrev_b32_e32 v94, 16, v95
	v_and_b32_e32 v95, 0xffff0000, v95
	v_pk_mul_f32 v[156:157], v[64:65], v[126:127] op_sel_hi:[0,1]
	v_pk_mul_f32 v[158:159], v[64:65], v[94:95] op_sel_hi:[0,1]
	v_cvt_pk_bf16_f32 v156, v156, v157
	v_cvt_pk_bf16_f32 v157, v158, v159
	global_load_dwordx4 v[186:189], v[112:113], off offset:192
	s_waitcnt vmcnt(6)
	v_mfma_f32_32x32x16_bf16 v[48:63], v[150:153], v[154:157], v[48:63]
	global_load_dwordx4 v[150:153], v[76:77], off offset:160
	s_waitcnt vmcnt(6)
	v_mfma_f32_32x32x16_bf16 v[32:47], v[174:177], v[154:157], v[32:47]
	global_load_dwordx4 v[174:177], v[114:115], off offset:160
	s_waitcnt vmcnt(6)
	v_mfma_f32_32x32x16_bf16 v[16:31], v[128:131], v[154:157], v[16:31]
	v_lshlrev_b32_e32 v128, 16, v88
	v_and_b32_e32 v129, 0xffff0000, v88
	v_mul_f32_e64 v130, v64, v128
	v_mul_f32_e64 v131, v64, v129
	v_lshlrev_b32_e32 v88, 16, v89
	v_and_b32_e32 v89, 0xffff0000, v89
	s_waitcnt vmcnt(5)
	v_mfma_f32_32x32x16_bf16 v[0:15], v[132:135], v[154:157], v[0:15]
	v_cvt_pk_bf16_f32 v132, v130, v131
	v_mul_f32_e64 v130, v64, v88
	v_mul_f32_e64 v131, v64, v89
	v_cvt_pk_bf16_f32 v133, v130, v131
	v_lshlrev_b32_e32 v130, 16, v90
	v_and_b32_e32 v131, 0xffff0000, v90
	v_lshlrev_b32_e32 v90, 16, v91
	v_and_b32_e32 v91, 0xffff0000, v91
	v_pk_mul_f32 v[134:135], v[64:65], v[130:131] op_sel_hi:[0,1]
	v_pk_mul_f32 v[154:155], v[64:65], v[90:91] op_sel_hi:[0,1]
	v_cvt_pk_bf16_f32 v134, v134, v135
	v_cvt_pk_bf16_f32 v135, v154, v155
	global_load_dwordx4 v[154:157], v[74:75], off offset:192
	s_waitcnt vmcnt(5)
	v_mfma_f32_32x32x16_bf16 v[48:63], v[178:181], v[132:135], v[48:63]
	global_load_dwordx4 v[178:181], v[76:77], off offset:192
	s_waitcnt vmcnt(5)
	v_mfma_f32_32x32x16_bf16 v[32:47], v[182:185], v[132:135], v[32:47]
	s_waitcnt vmcnt(3)
	v_mfma_f32_32x32x16_bf16 v[16:31], v[150:153], v[132:135], v[16:31]
	global_load_dwordx4 v[150:153], v[114:115], off offset:192
	global_load_dwordx4 v[182:185], v[112:113], off offset:224
	v_lshlrev_b32_e32 v112, 16, v84
	v_and_b32_e32 v113, 0xffff0000, v84
	v_lshlrev_b32_e32 v84, 16, v85
	v_and_b32_e32 v85, 0xffff0000, v85
	s_waitcnt vmcnt(4)
	v_mfma_f32_32x32x16_bf16 v[0:15], v[174:177], v[132:135], v[0:15]
	v_mul_f32_e64 v132, v64, v112
	v_mul_f32_e64 v133, v64, v113
	v_cvt_pk_bf16_f32 v174, v132, v133
	v_mul_f32_e64 v132, v64, v84
	v_mul_f32_e64 v133, v64, v85
	v_cvt_pk_bf16_f32 v175, v132, v133
	v_lshlrev_b32_e32 v132, 16, v86
	v_and_b32_e32 v133, 0xffff0000, v86
	v_pk_mul_f32 v[134:135], v[64:65], v[132:133] op_sel_hi:[0,1]
	v_lshlrev_b32_e32 v86, 16, v87
	v_and_b32_e32 v87, 0xffff0000, v87
	v_cvt_pk_bf16_f32 v176, v134, v135
	v_pk_mul_f32 v[134:135], v[64:65], v[86:87] op_sel_hi:[0,1]
	v_cvt_pk_bf16_f32 v177, v134, v135
	v_lshlrev_b32_e32 v134, 16, v80
	v_and_b32_e32 v135, 0xffff0000, v80
	v_mfma_f32_32x32x16_bf16 v[48:63], v[186:189], v[174:177], v[48:63]
	global_load_dwordx4 v[186:189], v[74:75], off offset:224
	global_load_dwordx4 v[190:193], v[76:77], off offset:224
	global_load_dwordx4 v[194:197], v[114:115], off offset:224
	v_lshl_add_u64 v[114:115], v[72:73], 0, v[160:161]
	v_add_co_u32_e32 v72, vcc, s20, v114
	v_lshlrev_b32_e32 v80, 16, v81
	s_nop 0
	v_addc_co_u32_e32 v73, vcc, 0, v115, vcc
	s_waitcnt vmcnt(6)
; __device__ __forceinline__ f32x16 mfma32(bf16x8 a, bf16x8 b, f32x16 c) { return __builtin_amdgcn_mfma_f32_32x32x16_bf16(a, b, c, 0, 0, 0); }
; __device__ void ret_out_item(const bf16_t* __restrict__ Qb, const bf16_t* __restrict__ Kb, bf16_t* Vb, const bf16_t* __restrict__ STf, const bf16_t* __restrict__ STb,
;                              int cidx, int head, float lgf2, float lgb2, LAS unsigned char* lds) {
;     ...
;   for (int dir = 0; dir < 2; ++dir) {
;     const float xi = dir ? __builtin_amdgcn_exp2f(lgb2 * (float)(128 - iloc)) : __builtin_amdgcn_exp2f(lgf2 * (float)(iloc + 1));
;     const bf16_t* sp = (dir ? STb : STf) + ((size_t)(cidx * 4 + head) * 256 + eh * 128 + il) * 128 + 8 * h;
; #pragma unroll
;     for (int kp = 0; kp < 4; ++kp) {
;       bf16x8 sf[2][4];
; #pragma unroll
;       for (int k2 = 0; k2 < 2; ++k2)
; #pragma unroll
;         for (int et = 0; et < 4; ++et) sf[k2][et] = *(const bf16x8*)(sp + (size_t)et * 32 * 128 + 16 * (2 * kp + k2));
; #pragma unroll
;       for (int k2 = 0; k2 < 2; ++k2) {
;         const bf16x8 sq = scale_frag(qf[2 * kp + k2], xi);
; #pragma unroll
;         for (int et = 0; et < 4; ++et) acc[et] = mfma32(sf[k2][et], sq, acc[et]);
;       }
;     }
	v_mfma_f32_32x32x16_bf16 v[32:47], v[154:157], v[174:177], v[32:47]
	global_load_dwordx4 v[154:157], v[114:115], off
	v_add_co_u32_e32 v76, vcc, s36, v114
	v_and_b32_e32 v81, 0xffff0000, v81
	s_nop 0
	v_addc_co_u32_e32 v77, vcc, 0, v115, vcc
	v_add_co_u32_e32 v74, vcc, s37, v114
	s_waitcnt vmcnt(5)
	v_mfma_f32_32x32x16_bf16 v[0:15], v[150:153], v[174:177], v[0:15]
	v_mul_f32_e64 v150, v64, v134
	v_mul_f32_e64 v151, v64, v135
	v_mul_f32_e64 v152, v64, v80
	v_mul_f32_e64 v153, v64, v81
	v_addc_co_u32_e32 v75, vcc, 0, v115, vcc
	v_cvt_pk_bf16_f32 v150, v150, v151
	v_cvt_pk_bf16_f32 v151, v152, v153
	v_pk_mul_f32 v[152:153], v[64:65], v[202:203] op_sel_hi:[0,1]
	v_pk_mul_f32 v[64:65], v[64:65], v[204:205] op_sel_hi:[0,1]
	global_load_dwordx4 v[198:201], v[72:73], off
	v_mfma_f32_32x32x16_bf16 v[16:31], v[178:181], v[174:177], v[16:31]
	global_load_dwordx4 v[178:181], v[76:77], off
	v_cvt_pk_bf16_f32 v152, v152, v153
	v_cvt_pk_bf16_f32 v153, v64, v65
	global_load_dwordx4 v[174:177], v[74:75], off
	v_sub_u32_e32 v64, 0x80, v147
	v_cvt_f32_ubyte0_e32 v64, v64
	v_mul_f32_e32 v64, v148, v64
	v_exp_f32_e32 v160, v64
	s_waitcnt vmcnt(7)
	v_mfma_f32_32x32x16_bf16 v[48:63], v[182:185], v[150:153], v[48:63]
	global_load_dwordx4 v[182:185], v[114:115], off offset:32
	v_mul_f32_e64 v64, v160, v66
	v_mul_f32_e64 v65, v160, v67
	v_mul_f32_e64 v66, v160, v68
	v_mul_f32_e64 v67, v160, v69
	v_cvt_pk_bf16_f32 v64, v64, v65
	v_cvt_pk_bf16_f32 v65, v66, v67
	v_pk_mul_f32 v[66:67], v[160:161], v[70:71] op_sel_hi:[0,1]
	v_pk_mul_f32 v[68:69], v[160:161], v[78:79] op_sel_hi:[0,1]
	v_cvt_pk_bf16_f32 v66, v66, v67
	v_cvt_pk_bf16_f32 v67, v68, v69
	global_load_dwordx4 v[68:71], v[76:77], off offset:32
	s_waitcnt vmcnt(8)
	v_mfma_f32_32x32x16_bf16 v[32:47], v[186:189], v[150:153], v[32:47]
	global_load_dwordx4 v[186:189], v[72:73], off offset:32
	v_mul_f32_e64 v78, v160, v108
	v_mul_f32_e64 v79, v160, v109
	v_cvt_pk_bf16_f32 v108, v78, v79
	v_mul_f32_e64 v78, v160, v104
	v_mul_f32_e64 v79, v160, v105
	v_cvt_pk_bf16_f32 v109, v78, v79
	v_pk_mul_f32 v[78:79], v[160:161], v[110:111] op_sel_hi:[0,1]
	v_cvt_pk_bf16_f32 v110, v78, v79
	s_waitcnt vmcnt(8)
	v_mfma_f32_32x32x16_bf16 v[16:31], v[190:193], v[150:153], v[16:31]
	v_mul_f32_e64 v78, v160, v106
	v_mul_f32_e64 v79, v160, v107
	global_load_dwordx4 v[104:107], v[76:77], off offset:64
	v_cvt_pk_bf16_f32 v111, v78, v79
	v_mul_f32_e64 v78, v160, v116
	v_mul_f32_e64 v79, v160, v117
	s_waitcnt vmcnt(8)
	v_mfma_f32_32x32x16_bf16 v[0:15], v[194:197], v[150:153], v[0:15]
	global_load_dwordx4 v[148:151], v[74:75], off offset:32
	s_waitcnt vmcnt(8)
	v_mfma_f32_32x32x16_bf16 v[48:63], v[154:157], v[64:67], v[48:63]
	global_load_dwordx4 v[152:155], v[114:115], off offset:64
	global_load_dwordx4 v[156:159], v[74:75], off offset:64
	s_waitcnt vmcnt(9)
	v_mfma_f32_32x32x16_bf16 v[32:47], v[198:201], v[64:67], v[32:47]
	s_waitcnt vmcnt(8)
	v_mfma_f32_32x32x16_bf16 v[16:31], v[178:181], v[64:67], v[16:31]
	s_waitcnt vmcnt(7)
	v_mfma_f32_32x32x16_bf16 v[0:15], v[174:177], v[64:67], v[0:15]
	global_load_dwordx4 v[64:67], v[72:73], off offset:64
	s_waitcnt vmcnt(6)
	v_mfma_f32_32x32x16_bf16 v[16:31], v[68:71], v[108:111], v[16:31]
	global_load_dwordx4 v[68:71], v[114:115], off offset:96
	global_load_dwordx4 v[174:177], v[72:73], off offset:96
	v_mfma_f32_32x32x16_bf16 v[48:63], v[182:185], v[108:111], v[48:63]
	s_waitcnt vmcnt(7)
	v_mfma_f32_32x32x16_bf16 v[32:47], v[186:189], v[108:111], v[32:47]
	s_waitcnt vmcnt(5)
	v_mfma_f32_32x32x16_bf16 v[0:15], v[148:151], v[108:111], v[0:15]
	v_cvt_pk_bf16_f32 v108, v78, v79
	v_mul_f32_e64 v78, v160, v100
	v_mul_f32_e64 v79, v160, v101
	v_cvt_pk_bf16_f32 v109, v78, v79
	v_mul_f32_e64 v78, v160, v118
	v_mul_f32_e64 v79, v160, v119
	v_cvt_pk_bf16_f32 v110, v78, v79
	v_pk_mul_f32 v[78:79], v[160:161], v[102:103] op_sel_hi:[0,1]
	global_load_dwordx4 v[100:103], v[76:77], off offset:96
	v_cvt_pk_bf16_f32 v111, v78, v79
	v_pk_mul_f32 v[78:79], v[160:161], v[120:121] op_sel_hi:[0,1]
	s_waitcnt vmcnt(5)
	v_mfma_f32_32x32x16_bf16 v[48:63], v[152:155], v[108:111], v[48:63]
	s_waitcnt vmcnt(3)
	v_mfma_f32_32x32x16_bf16 v[32:47], v[64:67], v[108:111], v[32:47]
	global_load_dwordx4 v[64:67], v[74:75], off offset:96
	v_mfma_f32_32x32x16_bf16 v[16:31], v[104:107], v[108:111], v[16:31]
	global_load_dwordx4 v[104:107], v[114:115], off offset:128
	v_mfma_f32_32x32x16_bf16 v[0:15], v[156:159], v[108:111], v[0:15]
	v_cvt_pk_bf16_f32 v108, v78, v79
	v_mul_f32_e64 v78, v160, v96
	v_mul_f32_e64 v79, v160, v97
	v_cvt_pk_bf16_f32 v109, v78, v79
	v_mul_f32_e64 v78, v160, v122
	v_mul_f32_e64 v79, v160, v123
	v_cvt_pk_bf16_f32 v110, v78, v79
	v_pk_mul_f32 v[78:79], v[160:161], v[98:99] op_sel_hi:[0,1]
	v_cvt_pk_bf16_f32 v111, v78, v79
	global_load_dwordx4 v[96:99], v[76:77], off offset:128
	v_pk_mul_f32 v[78:79], v[160:161], v[124:125] op_sel_hi:[0,1]
	s_waitcnt vmcnt(5)
	v_mfma_f32_32x32x16_bf16 v[48:63], v[68:71], v[108:111], v[48:63]
	global_load_dwordx4 v[68:71], v[72:73], off offset:128
	s_waitcnt vmcnt(4)
	v_mfma_f32_32x32x16_bf16 v[16:31], v[100:103], v[108:111], v[16:31]
	global_load_dwordx4 v[100:103], v[74:75], off offset:128
	global_load_dwordx4 v[116:119], v[114:115], off offset:160
	v_mfma_f32_32x32x16_bf16 v[32:47], v[174:177], v[108:111], v[32:47]
	s_waitcnt vmcnt(5)
	v_mfma_f32_32x32x16_bf16 v[0:15], v[64:67], v[108:111], v[0:15]
	v_mul_f32_e64 v66, v160, v92
	v_mul_f32_e64 v67, v160, v93
	v_cvt_pk_bf16_f32 v64, v78, v79
	v_cvt_pk_bf16_f32 v65, v66, v67
	v_mul_f32_e64 v66, v160, v126
	v_mul_f32_e64 v67, v160, v127
	v_pk_mul_f32 v[78:79], v[160:161], v[94:95] op_sel_hi:[0,1]
	v_cvt_pk_bf16_f32 v66, v66, v67
	v_cvt_pk_bf16_f32 v67, v78, v79
	global_load_dwordx4 v[92:95], v[72:73], off offset:160
	v_pk_mul_f32 v[78:79], v[160:161], v[128:129] op_sel_hi:[0,1]
	s_waitcnt vmcnt(3)
; #define LAS __attribute__((address_space(3)))
; __device__ __forceinline__ f32x16 mfma32(bf16x8 a, bf16x8 b, f32x16 c) { return __builtin_amdgcn_mfma_f32_32x32x16_bf16(a, b, c, 0, 0, 0); }
; __device__ void ret_out_item(const bf16_t* __restrict__ Qb, const bf16_t* __restrict__ Kb, bf16_t* Vb, const bf16_t* __restrict__ STf, const bf16_t* __restrict__ STb,
;                              int cidx, int head, float lgf2, float lgb2, LAS unsigned char* lds) {
;     ...
;   for (int dir = 0; dir < 2; ++dir) {
;     const float xi = dir ? __builtin_amdgcn_exp2f(lgb2 * (float)(128 - iloc)) : __builtin_amdgcn_exp2f(lgf2 * (float)(iloc + 1));
;     const bf16_t* sp = (dir ? STb : STf) + ((size_t)(cidx * 4 + head) * 256 + eh * 128 + il) * 128 + 8 * h;
; #pragma unroll
;     for (int kp = 0; kp < 4; ++kp) {
;       bf16x8 sf[2][4];
; #pragma unroll
;       for (int k2 = 0; k2 < 2; ++k2)
; #pragma unroll
;         for (int et = 0; et < 4; ++et) sf[k2][et] = *(const bf16x8*)(sp + (size_t)et * 32 * 128 + 16 * (2 * kp + k2));
; #pragma unroll
;       for (int k2 = 0; k2 < 2; ++k2) {
;         const bf16x8 sq = scale_frag(qf[2 * kp + k2], xi);
; #pragma unroll
;         for (int et = 0; et < 4; ++et) acc[et] = mfma32(sf[k2][et], sq, acc[et]);
;       }
;     }
;   }
;   float ss = 0.f;
; #pragma unroll
;   for (int et = 0; et < 4; ++et)
; #pragma unroll
;     for (int r = 0; r < 16; ++r) ss += acc[et][r] * acc[et][r];
;   ss += __shfl_xor(ss, 32);
;   LAS float* red = (LAS float*)(lds + ORED);
;   if (h == 0) red[eh * 128 + iloc] = ss;
	v_mfma_f32_32x32x16_bf16 v[32:47], v[68:71], v[64:67], v[32:47]
	global_load_dwordx4 v[68:71], v[76:77], off offset:160
	v_mfma_f32_32x32x16_bf16 v[48:63], v[104:107], v[64:67], v[48:63]
	v_cvt_pk_bf16_f32 v104, v78, v79
	v_mul_f32_e64 v78, v160, v88
	v_mul_f32_e64 v79, v160, v89
	v_cvt_pk_bf16_f32 v105, v78, v79
	v_mul_f32_e64 v78, v160, v130
	v_mul_f32_e64 v79, v160, v131
	v_cvt_pk_bf16_f32 v106, v78, v79
	v_pk_mul_f32 v[78:79], v[160:161], v[90:91] op_sel_hi:[0,1]
	v_cvt_pk_bf16_f32 v107, v78, v79
	v_mfma_f32_32x32x16_bf16 v[16:31], v[96:99], v[64:67], v[16:31]
	global_load_dwordx4 v[96:99], v[74:75], off offset:160
	global_load_dwordx4 v[88:91], v[72:73], off offset:192
	v_mul_f32_e64 v78, v160, v112
	v_mul_f32_e64 v79, v160, v113
	v_cvt_pk_bf16_f32 v82, v78, v79
	v_pk_mul_f32 v[78:79], v[160:161], v[84:85] op_sel_hi:[0,1]
	v_cvt_pk_bf16_f32 v83, v78, v79
	v_pk_mul_f32 v[78:79], v[160:161], v[132:133] op_sel_hi:[0,1]
	s_waitcnt vmcnt(5)
	v_mfma_f32_32x32x16_bf16 v[0:15], v[100:103], v[64:67], v[0:15]
	global_load_dwordx4 v[64:67], v[114:115], off offset:192
	v_cvt_pk_bf16_f32 v84, v78, v79
	v_mul_f32_e64 v78, v160, v86
	v_mul_f32_e64 v79, v160, v87
	v_cvt_pk_bf16_f32 v85, v78, v79
	v_pk_mul_f32 v[86:87], v[160:161], v[134:135] op_sel_hi:[0,1]
	s_waitcnt vmcnt(5)
	v_mfma_f32_32x32x16_bf16 v[48:63], v[116:119], v[104:107], v[48:63]
	s_waitcnt vmcnt(4)
	v_mfma_f32_32x32x16_bf16 v[32:47], v[92:95], v[104:107], v[32:47]
	global_load_dwordx4 v[92:95], v[76:77], off offset:192
	s_waitcnt vmcnt(4)
	v_mfma_f32_32x32x16_bf16 v[16:31], v[68:71], v[104:107], v[16:31]
	global_load_dwordx4 v[68:71], v[74:75], off offset:192
	global_load_dwordx4 v[100:103], v[114:115], off offset:224
	s_nop 0
	global_load_dwordx4 v[76:79], v[76:77], off offset:224
	s_waitcnt vmcnt(4)
	v_mfma_f32_32x32x16_bf16 v[48:63], v[64:67], v[82:85], v[48:63]
	global_load_dwordx4 v[64:67], v[72:73], off offset:224
	s_nop 0
	global_load_dwordx4 v[72:75], v[74:75], off offset:224
	v_mfma_f32_32x32x16_bf16 v[0:15], v[96:99], v[104:107], v[0:15]
	s_waitcnt vmcnt(4)
	v_mfma_f32_32x32x16_bf16 v[0:15], v[68:71], v[82:85], v[0:15]
	v_mul_f32_e64 v70, v160, v80
	v_mul_f32_e64 v71, v160, v81
	v_cvt_pk_bf16_f32 v69, v70, v71
	v_mul_f32_e64 v70, v160, v202
	v_mul_f32_e64 v71, v160, v203
	v_pk_mul_f32 v[80:81], v[160:161], v[204:205] op_sel_hi:[0,1]
	v_cvt_pk_bf16_f32 v68, v86, v87
	v_cvt_pk_bf16_f32 v70, v70, v71
	v_cvt_pk_bf16_f32 v71, v80, v81
	v_mfma_f32_32x32x16_bf16 v[32:47], v[88:91], v[82:85], v[32:47]
	s_waitcnt vmcnt(3)
	v_mfma_f32_32x32x16_bf16 v[48:63], v[100:103], v[68:71], v[48:63]
	s_waitcnt vmcnt(1)
	v_mfma_f32_32x32x16_bf16 v[32:47], v[64:67], v[68:71], v[32:47]
	s_nop 9
	v_mul_f32_e32 v64, v49, v49
	v_fmac_f32_e32 v64, v48, v48
	v_fmac_f32_e32 v64, v50, v50
	v_fmac_f32_e32 v64, v51, v51
	v_fmac_f32_e32 v64, v52, v52
	v_fmac_f32_e32 v64, v53, v53
	v_fmac_f32_e32 v64, v54, v54
	v_fmac_f32_e32 v64, v55, v55
	v_fmac_f32_e32 v64, v56, v56
	v_fmac_f32_e32 v64, v57, v57
	v_fmac_f32_e32 v64, v58, v58
	v_fmac_f32_e32 v64, v59, v59
	v_fmac_f32_e32 v64, v60, v60
	v_fmac_f32_e32 v64, v61, v61
	v_fmac_f32_e32 v64, v62, v62
	v_fmac_f32_e32 v64, v63, v63
	v_mfma_f32_32x32x16_bf16 v[16:31], v[92:95], v[82:85], v[16:31]
	v_fmac_f32_e32 v64, v32, v32
	v_fmac_f32_e32 v64, v33, v33
	v_fmac_f32_e32 v64, v34, v34
	v_fmac_f32_e32 v64, v35, v35
	v_fmac_f32_e32 v64, v36, v36
	v_fmac_f32_e32 v64, v37, v37
	v_fmac_f32_e32 v64, v38, v38
	v_fmac_f32_e32 v64, v39, v39
	v_mfma_f32_32x32x16_bf16 v[16:31], v[76:79], v[68:71], v[16:31]
	v_fmac_f32_e32 v64, v40, v40
	v_fmac_f32_e32 v64, v41, v41
	v_fmac_f32_e32 v64, v42, v42
	v_fmac_f32_e32 v64, v43, v43
	v_fmac_f32_e32 v64, v44, v44
	v_fmac_f32_e32 v64, v45, v45
	v_fmac_f32_e32 v64, v46, v46
	v_fmac_f32_e32 v64, v47, v47
	s_nop 3
	v_fmac_f32_e32 v64, v16, v16
	v_fmac_f32_e32 v64, v17, v17
	v_fmac_f32_e32 v64, v18, v18
	v_fmac_f32_e32 v64, v19, v19
	v_fmac_f32_e32 v64, v20, v20
	v_fmac_f32_e32 v64, v21, v21
	v_fmac_f32_e32 v64, v22, v22
	v_fmac_f32_e32 v64, v23, v23
	s_waitcnt vmcnt(0)
	v_mfma_f32_32x32x16_bf16 v[0:15], v[72:75], v[68:71], v[0:15]
	v_fmac_f32_e32 v64, v24, v24
	v_fmac_f32_e32 v64, v25, v25
	v_fmac_f32_e32 v64, v26, v26
	v_fmac_f32_e32 v64, v27, v27
	v_fmac_f32_e32 v64, v28, v28
	v_fmac_f32_e32 v64, v29, v29
	v_fmac_f32_e32 v64, v30, v30
	v_fmac_f32_e32 v64, v31, v31
	s_nop 3
	v_fmac_f32_e32 v64, v0, v0
	v_fmac_f32_e32 v64, v1, v1
	v_fmac_f32_e32 v64, v2, v2
	v_fmac_f32_e32 v64, v3, v3
	v_fmac_f32_e32 v64, v4, v4
	v_fmac_f32_e32 v64, v5, v5
	v_fmac_f32_e32 v64, v6, v6
	v_fmac_f32_e32 v64, v7, v7
	v_fmac_f32_e32 v64, v8, v8
	v_fmac_f32_e32 v64, v9, v9
	v_fmac_f32_e32 v64, v10, v10
	v_fmac_f32_e32 v64, v11, v11
	v_and_b32_e32 v66, 64, v219
	v_fmac_f32_e32 v64, v12, v12
	v_xor_b32_e32 v65, 32, v219
	v_add_u32_e32 v66, 64, v66
	v_fmac_f32_e32 v64, v13, v13
	v_cmp_lt_i32_e32 vcc, v65, v66
	v_fmac_f32_e32 v64, v14, v14
	v_fmac_f32_e32 v64, v15, v15
	v_cndmask_b32_e32 v65, v219, v65, vcc
	v_lshlrev_b32_e32 v65, 2, v65
	ds_bpermute_b32 v65, v65, v64
	v_cmp_eq_u32_e32 vcc, 0, v146
	s_and_saveexec_b64 s[34:35], vcc
	s_cbranch_execz .LBB0_623
	s_waitcnt lgkmcnt(0)
	v_add_f32_e32 v64, v64, v65
	s_add_i32 s20, 0, 0x12000
	v_lshlrev_b32_e32 v65, 2, v136
	v_lshlrev_b32_e32 v66, 2, v147
	v_add3_u32 v65, s20, v65, v66
	ds_write_b32 v65, v64
	s_branch .LBB0_623
